# K-loop 4x32-MFMA step merge applied to swiglu, proj, act, gate, softmax GEMM loops (EpiF32 loop unchanged: accumulator rotation conflicts)
# speedup vs baseline: 1.0223x; 1.0065x over previous
; __device__ __forceinline__ int otid() { int t = threadIdx.x; asm volatile("" : "+v"(t)); return t; }
; #define PG8_STAGE(bufoff, gbase, voff) do { _Pragma("unroll") for (int _i = 0; _i < 2; ++_i) \
;         __builtin_amdgcn_global_load_lds((const unsigned*)((const char*)(gbase) + (voff)[_i]), (LAS unsigned*)(lds + (bufoff) + ldsw + _i * 8192), 16, 0, 0); } while (0)
; #define PG8_WAIT_V(n) asm volatile("s_waitcnt vmcnt(" #n ")" ::: "memory")
; #define PG8_BAR __builtin_amdgcn_s_barrier()
;     __device__ __forceinline__ Pre prefetch(const Unit& u, int wr, int fr) const { return pre_rows(ss, u.pm * 256 + wr * 64 + (int)(threadIdx.x & 63)); }
;     __device__ __forceinline__ Pre prefetch(const Unit& u, int wr, int fr) const { return pre_rows(ss, u.pm * 256 + wr * 64 + (int)(threadIdx.x & 63)); }
; template <class Epi>
; __device__ __forceinline__ void gemm_phase(LAS unsigned char* lds, const Gemm g, const Sched& S, const Epi& E) {
;     const int tid = otid(), wid = __builtin_amdgcn_readfirstlane(tid >> 6), lane = tid & 63, wr = wid >> 2, wc = wid & 3, fr = lane & 15, fq = lane >> 4;
;     const int nt = g.K / BK;
;     unsigned voffA[2], voffB[2];
; #pragma unroll
;     for (int i = 0; i < 2; ++i) { int R, C; stage_rc(tid * 16 + i * 8192, R, C); const int Rb = Epi::PERM ? ((R & ~31) + perm32(R & 31)) : R;
;         voffA[i] = (unsigned)(R * g.lda + C) * 2u; voffB[i] = (unsigned)(Rb * g.ldb + C) * 2u; }
;     const size_t kstep = (size_t)(BK * 2);
;     const size_t hstepA = (size_t)HALF * g.lda * 2, hstepB = (size_t)HALF * g.ldb * 2;
;     const unsigned ldsw = (unsigned)wid * 1024u;
;     const int aoff = lds_byte(wr * 64 + fr, fq * 8), boff = lds_byte(wc * 32 + fr, fq * 8);
;     ...
;     PG8_STAGE(PG8_SB(0, 0), cB, voffB); PG8_STAGE(PG8_SA(0, 0), cA, voffA); PG8_STAGE(PG8_SB(0, 1), cB + hstepB, voffB); PG8_STAGE(PG8_SA(0, 1), cA + hstepA, voffA);
;     if (wr == 1) PG8_BAR;
;     PG8_WAIT_V(4); PG8_BAR;
;     PG8_STAGE(PG8_SB(1, 0), cB + kstep, voffB); PG8_STAGE(PG8_SA(1, 0), cA + kstep, voffA); PG8_STAGE(PG8_SB(1, 1), cB + hstepB + kstep, voffB);
;     PG8_WAIT_V(6); PG8_BAR;
;     for (;;) {
;         const Pre pre = E.prefetch(cur, wr, fr);
;         const bool has_next = S.next(ui + 1, nxt);
;         const char* nA = has_next ? (const char*)g.A + nxt.ao : cA; const char* nB = has_next ? (const char*)g.Bt + nxt.bo : cB;
.LBB0_386:
	s_add_i32 m0, s42, 0x18000
	v_lshl_add_u64 v[2:3], v[2:3], 0, s[60:61]
	s_waitcnt vmcnt(0)
	s_barrier
	global_load_lds_dwordx4 v[2:3], off
	v_lshl_add_u64 v[2:3], v[4:5], 0, s[60:61]
	s_add_i32 m0, s42, 0x1a000
	s_add_i32 s67, s42, 0x8000
	global_load_lds_dwordx4 v[2:3], off
	v_lshl_add_u64 v[2:3], v[6:7], 0, s[60:61]
	s_mov_b32 m0, s67
	s_add_i32 s2, s42, 0xa000
	global_load_lds_dwordx4 v[2:3], off
	v_lshl_add_u64 v[2:3], v[8:9], 0, s[60:61]
	s_mov_b32 m0, s2
	v_bfe_u32 v20, v17, 4, 2
	global_load_lds_dwordx4 v[2:3], off
	s_add_i32 m0, s42, 0x1c000
	v_lshl_add_u64 v[2:3], v[10:11], 0, s[60:61]
	global_load_lds_dwordx4 v[2:3], off
	v_lshl_add_u64 v[2:3], v[12:13], 0, s[60:61]
	s_add_i32 m0, s42, 0x1e000
	v_and_b32_e32 v150, 15, v17
	global_load_lds_dwordx4 v[2:3], off
	v_lshlrev_b32_e32 v22, 4, v20
	v_lshlrev_b32_e32 v17, 2, v17
	s_and_b32 s3, s0, 3
	s_lshl_b32 s0, s1, 6
	v_lshl_or_b32 v22, v150, 6, v22
	s_lshl_b32 s1, s1, 13
	v_and_b32_e32 v17, 32, v17
	v_readlane_b32 s8, v253, 61
	v_bitop3_b32 v23, v22, s1, v17 bitop3:0xde
	s_lshl_b32 s1, s3, 12
	s_add_i32 s71, s73, -2
	v_readlane_b32 s9, v253, 62
	s_cmp_eq_u64 s[8:9], 0
	s_cselect_b64 s[80:81], -1, 0
	s_cmp_lg_u64 s[8:9], 0
	v_readlane_b32 s8, v254, 13
	s_cselect_b64 s[82:83], -1, 0
	s_ashr_i32 s40, s8, 31
	v_readlane_b32 s8, v253, 30
	s_lshr_b32 s8, s54, 3
	v_readlane_b32 s9, v253, 31
	v_writelane_b32 v254, s8, 47
	s_add_i32 s8, s8, 1
	v_writelane_b32 v254, s8, 31
	s_mov_b32 s27, s9
	v_readlane_b32 s8, v254, 5
	v_readlane_b32 s9, v254, 37
	s_mul_i32 s56, s8, s9
	v_cvt_f32_u32_e32 v3, s56
	v_or_b32_e32 v151, s0, v150
	v_lshlrev_b32_e32 v21, 3, v20
	v_and_b32_e32 v2, 63, v219
	v_rcp_iflag_f32_e32 v3, v3
	v_or_b32_e32 v153, s0, v2
	v_lshlrev_b32_e32 v154, 4, v151
	v_lshl_or_b32 v2, s3, 5, v21
	s_add_i32 s8, 0, 0x20000
	s_lshl_b32 s3, s3, 2
	s_add_i32 s51, s8, s3
	v_add_u32_e32 v155, s8, v154
	v_readlane_b32 s8, v253, 21
	v_mul_f32_e32 v3, 0x4f7ffffe, v3
	v_cvt_u32_f32_e32 v3, v3
	v_add_u32_e32 v157, s8, v154
	v_readlane_b32 s8, v253, 22
	v_add_u32_e32 v156, s3, v155
	v_add_u32_e32 v158, s3, v157
	v_add_u32_e32 v159, s8, v154
	v_readlane_b32 s8, v253, 23
	v_add_u32_e32 v160, s3, v159
	v_add_u32_e32 v0, v15, v0
	v_add_u32_e32 v161, s8, v154
	v_readlane_b32 s8, v253, 24
	v_add_u32_e32 v162, s3, v161
	v_add_lshl_u32 v0, v0, v14, 1
	v_add_u32_e32 v163, s8, v154
	v_readlane_b32 s8, v253, 25
	v_add_u32_e32 v164, s3, v163
	s_waitcnt vmcnt(6)
	v_lshl_add_u64 v[138:139], s[4:5], 0, v[0:1]
	v_add_u32_e32 v165, s8, v154
	v_readlane_b32 s8, v253, 26
	v_add_u32_e32 v166, s3, v165
	v_add_u32_e32 v0, v19, v16
	v_add_u32_e32 v167, s8, v154
	v_readlane_b32 s8, v253, 27
	v_add_u32_e32 v168, s3, v167
	v_add_lshl_u32 v0, v0, v18, 1
	v_add_u32_e32 v169, s8, v154
	v_readfirstlane_b32 s8, v3
	v_cvt_f32_u32_e32 v3, s25
	v_add_u32_e32 v170, s3, v169
	s_sub_i32 s3, 0, s56
	s_mul_i32 s3, s3, s8
	v_rcp_iflag_f32_e32 v3, v3
	s_mul_hi_u32 s3, s8, s3
	s_add_i32 s3, s8, s3
	v_writelane_b32 v254, s3, 33
	v_mul_f32_e32 v3, 0x4f7ffffe, v3
	v_cvt_u32_f32_e32 v3, v3
	s_sub_i32 s3, 0, s25
	v_bitop3_b32 v152, v22, s1, v17 bitop3:0xde
	s_mov_b32 s38, 0
	v_readfirstlane_b32 s8, v3
	s_mul_i32 s3, s3, s8
	s_mul_hi_u32 s3, s8, s3
	s_add_i32 s3, s8, s3
	v_cmp_eq_u32_e64 s[0:1], 0, v20
	s_and_b32 s41, s54, 7
	v_writelane_b32 v254, s3, 35
	v_lshl_add_u64 v[140:141], s[4:5], 0, v[0:1]
	v_add_u32_e32 v171, 0, v23
	v_lshlrev_b32_e32 v0, 1, v2
	s_barrier
	s_branch .LBB0_388

; #define PG8_STAGE(bufoff, gbase, voff) do { _Pragma("unroll") for (int _i = 0; _i < 2; ++_i) \
;         __builtin_amdgcn_global_load_lds((const unsigned*)((const char*)(gbase) + (voff)[_i]), (LAS unsigned*)(lds + (bufoff) + ldsw + _i * 8192), 16, 0, 0); } while (0)
; #define PG8_LDA(dst, b, h) do { _Pragma("unroll") for (int m = 0; m < 4; ++m) _Pragma("unroll") for (int k = 0; k < 2; ++k) dst[m][k] = *(const LAS bf16x8*)(lds + PG8_SA(b, h) + aoff + m * 2048 + k * 1024); } while (0)
; #define PG8_LDB(dst, b, h) do { _Pragma("unroll") for (int n = 0; n < 2; ++n) _Pragma("unroll") for (int k = 0; k < 2; ++k) dst[n][k] = *(const LAS bf16x8*)(lds + PG8_SB(b, h) + boff + n * 2048 + k * 1024); } while (0)
; #define PG8_MMA(ai, bj, At, Bt) do { __builtin_amdgcn_s_setprio(1); _Pragma("unroll") for (int m = 0; m < 4; ++m) _Pragma("unroll") for (int n = 0; n < 2; ++n) _Pragma("unroll") for (int k = 0; k < 2; ++k) \
;         acc[ai][bj][m][n] = __builtin_amdgcn_mfma_f32_16x16x32_bf16(Bt[n][k], At[m][k], acc[ai][bj][m][n], 0, 0, 0); __builtin_amdgcn_s_setprio(0); } while (0)
; #define PG8_WAIT_L(n) asm volatile("s_waitcnt lgkmcnt(" #n ")" ::: "memory")
; #define PG8_BAR __builtin_amdgcn_s_barrier()
; #define PG8_SCHED __builtin_amdgcn_sched_barrier(0)
; template <class Epi>
; __device__ __forceinline__ void gemm_phase(LAS unsigned char* lds, const Gemm g, const Sched& S, const Epi& E) {
;     ...
;         for (int t = 0; t < nt; t += 2) {
;             const bool last = (t == nt - 2);
;             const char* a1 = cA + (size_t)(t + 1) * kstep;
;             const char* a2 = last ? nA : cA + (size_t)(t + 2) * kstep; const char* b2 = last ? nB : cB + (size_t)(t + 2) * kstep;
;             const char* a3 = a2 + kstep; const char* b3 = b2 + kstep;
;             PG8_LDB(B0, 0, 0); PG8_SCHED; PG8_LDA(At, 0, 0); PG8_STAGE(PG8_SA(1, 1), a1 + hstepA, voffA);
;             PG8_WAIT_L(8); PG8_BAR; PG8_WAIT_L(0); PG8_MMA(0, 0, At, B0); PG8_BAR; PG8_SCHED;
;             PG8_LDB(B1, 0, 1); PG8_STAGE(PG8_SB(0, 0), b2, voffB);
;             PG8_BAR; PG8_WAIT_L(0); PG8_MMA(0, 1, At, B1); PG8_BAR;
;             PG8_LDA(At, 0, 1); PG8_STAGE(PG8_SA(0, 0), a2, voffA);
.LBB0_400:
	s_add_i32 s14, s66, 2
	s_add_u32 s8, s92, 0x80
	s_addc_u32 s9, s93, 0
	s_add_i32 s15, 0, 0x10000
	v_add_u32_e32 v148, s15, v152
	ds_read_b128 v[144:147], v148
	ds_read_b128 v[172:175], v148 offset:1024
	ds_read_b128 v[176:179], v148 offset:2048
	ds_read_b128 v[180:183], v148 offset:3072
	s_cmp_eq_u32 s71, s66
	s_cselect_b32 s95, s55, s9
	s_cselect_b32 s94, s57, s8
	s_cselect_b32 s97, s59, s35
	s_cselect_b32 s96, s65, s34
	v_lshl_add_u64 v[148:149], s[92:93], 0, v[138:139]
	s_add_i32 m0, s42, 0xc000
	ds_read_b128 v[184:187], v171
	ds_read_b128 v[188:191], v171 offset:1024
	ds_read_b128 v[196:199], v171 offset:2048
	ds_read_b128 v[200:203], v171 offset:3072
	ds_read_b128 v[204:207], v171 offset:4096
	ds_read_b128 v[208:211], v171 offset:5120
	ds_read_b128 v[212:215], v171 offset:6144
	ds_read_b128 v[222:225], v171 offset:7168
	global_load_lds_dwordx4 v[148:149], off
	v_lshl_add_u64 v[148:149], s[92:93], 0, v[140:141]
	s_add_i32 m0, s42, 0xe000
	s_nop 0
	global_load_lds_dwordx4 v[148:149], off
	s_add_i32 s8, 0, 0x14000
	v_add_u32_e32 v148, s8, v152
	ds_read_b128 v[226:229], v148
	ds_read_b128 v[230:233], v148 offset:1024
	ds_read_b128 v[234:237], v148 offset:2048
	ds_read_b128 v[238:241], v148 offset:3072
	s_waitcnt vmcnt(8)
	s_waitcnt lgkmcnt(0)
	s_barrier
	s_setprio 1
	v_mfma_f32_16x16x32_bf16 v[126:129], v[144:147], v[184:187], v[126:129]
	v_mfma_f32_16x16x32_bf16 v[122:125], v[176:179], v[184:187], v[122:125]
	v_mfma_f32_16x16x32_bf16 v[110:113], v[144:147], v[196:199], v[110:113]
	v_mfma_f32_16x16x32_bf16 v[106:109], v[176:179], v[196:199], v[106:109]
	v_mfma_f32_16x16x32_bf16 v[94:97], v[144:147], v[204:207], v[94:97]
	v_mfma_f32_16x16x32_bf16 v[90:93], v[176:179], v[204:207], v[90:93]
	v_mfma_f32_16x16x32_bf16 v[78:81], v[144:147], v[212:215], v[78:81]
	v_mfma_f32_16x16x32_bf16 v[74:77], v[176:179], v[212:215], v[74:77]
	v_mfma_f32_16x16x32_bf16 v[126:129], v[172:175], v[188:191], v[126:129]
	v_mfma_f32_16x16x32_bf16 v[122:125], v[180:183], v[188:191], v[122:125]
	v_mfma_f32_16x16x32_bf16 v[110:113], v[172:175], v[200:203], v[110:113]
	v_mfma_f32_16x16x32_bf16 v[106:109], v[180:183], v[200:203], v[106:109]
	v_mfma_f32_16x16x32_bf16 v[94:97], v[172:175], v[208:211], v[94:97]
	v_mfma_f32_16x16x32_bf16 v[90:93], v[180:183], v[208:211], v[90:93]
	v_mfma_f32_16x16x32_bf16 v[78:81], v[172:175], v[222:225], v[78:81]
	v_mfma_f32_16x16x32_bf16 v[74:77], v[180:183], v[222:225], v[74:77]
	v_mfma_f32_16x16x32_bf16 v[118:121], v[226:229], v[184:187], v[118:121]
	v_mfma_f32_16x16x32_bf16 v[114:117], v[234:237], v[184:187], v[114:117]
	v_mfma_f32_16x16x32_bf16 v[102:105], v[226:229], v[196:199], v[102:105]
	v_mfma_f32_16x16x32_bf16 v[98:101], v[234:237], v[196:199], v[98:101]
	v_mfma_f32_16x16x32_bf16 v[86:89], v[226:229], v[204:207], v[86:89]
	v_mfma_f32_16x16x32_bf16 v[82:85], v[234:237], v[204:207], v[82:85]
	v_mfma_f32_16x16x32_bf16 v[70:73], v[226:229], v[212:215], v[70:73]
	v_mfma_f32_16x16x32_bf16 v[66:69], v[234:237], v[212:215], v[66:69]
	v_mfma_f32_16x16x32_bf16 v[118:121], v[230:233], v[188:191], v[118:121]
	v_mfma_f32_16x16x32_bf16 v[114:117], v[238:241], v[188:191], v[114:117]
	v_mfma_f32_16x16x32_bf16 v[102:105], v[230:233], v[200:203], v[102:105]
	v_mfma_f32_16x16x32_bf16 v[98:101], v[238:241], v[200:203], v[98:101]
	v_mfma_f32_16x16x32_bf16 v[86:89], v[230:233], v[208:211], v[86:89]
	v_mfma_f32_16x16x32_bf16 v[82:85], v[238:241], v[208:211], v[82:85]
	v_mfma_f32_16x16x32_bf16 v[70:73], v[230:233], v[222:225], v[70:73]
	v_mfma_f32_16x16x32_bf16 v[66:69], v[238:241], v[222:225], v[66:69]
	s_setprio 0
	s_barrier
	s_add_i32 s9, s15, s39
	v_lshl_add_u64 v[148:149], s[96:97], 0, v[132:133]
	s_mov_b32 m0, s9
	v_lshl_add_u64 v[192:193], s[96:97], 0, v[136:137]
	global_load_lds_dwordx4 v[148:149], off
	s_add_i32 m0, s9, 0x2000
	s_nop 0
	global_load_lds_dwordx4 v[192:193], off
	s_mov_b32 m0, s42
	v_lshl_add_u64 v[194:195], s[94:95], 0, v[130:131]
	ds_read_b128 v[184:187], v171 offset:16384
	ds_read_b128 v[188:191], v171 offset:17408
	ds_read_b128 v[196:199], v171 offset:18432
	ds_read_b128 v[200:203], v171 offset:19456
	ds_read_b128 v[204:207], v171 offset:20480
	ds_read_b128 v[208:211], v171 offset:21504
	ds_read_b128 v[212:215], v171 offset:22528
	ds_read_b128 v[222:225], v171 offset:23552
	global_load_lds_dwordx4 v[194:195], off
	v_lshl_add_u64 v[216:217], s[94:95], 0, v[134:135]
	s_mov_b32 m0, s43
	s_nop 0
	global_load_lds_dwordx4 v[216:217], off
	s_add_u32 s96, s96, s78
	s_addc_u32 s97, s97, s79
	s_add_i32 s8, s8, s39
	v_lshl_add_u64 v[242:243], s[96:97], 0, v[132:133]
	s_mov_b32 m0, s8
	v_lshl_add_u64 v[244:245], s[96:97], 0, v[136:137]
	global_load_lds_dwordx4 v[242:243], off
	s_add_i32 m0, s8, 0x2000
	s_nop 0
	global_load_lds_dwordx4 v[244:245], off
	s_waitcnt vmcnt(8)
	s_waitcnt lgkmcnt(0)
	s_barrier
; #define PG8_STAGE(bufoff, gbase, voff) do { _Pragma("unroll") for (int _i = 0; _i < 2; ++_i) \
;         __builtin_amdgcn_global_load_lds((const unsigned*)((const char*)(gbase) + (voff)[_i]), (LAS unsigned*)(lds + (bufoff) + ldsw + _i * 8192), 16, 0, 0); } while (0)
; #define PG8_LDA(dst, b, h) do { _Pragma("unroll") for (int m = 0; m < 4; ++m) _Pragma("unroll") for (int k = 0; k < 2; ++k) dst[m][k] = *(const LAS bf16x8*)(lds + PG8_SA(b, h) + aoff + m * 2048 + k * 1024); } while (0)
; #define PG8_LDB(dst, b, h) do { _Pragma("unroll") for (int n = 0; n < 2; ++n) _Pragma("unroll") for (int k = 0; k < 2; ++k) dst[n][k] = *(const LAS bf16x8*)(lds + PG8_SB(b, h) + boff + n * 2048 + k * 1024); } while (0)
; #define PG8_MMA(ai, bj, At, Bt) do { __builtin_amdgcn_s_setprio(1); _Pragma("unroll") for (int m = 0; m < 4; ++m) _Pragma("unroll") for (int n = 0; n < 2; ++n) _Pragma("unroll") for (int k = 0; k < 2; ++k) \
;         acc[ai][bj][m][n] = __builtin_amdgcn_mfma_f32_16x16x32_bf16(Bt[n][k], At[m][k], acc[ai][bj][m][n], 0, 0, 0); __builtin_amdgcn_s_setprio(0); } while (0)
; #define PG8_WAIT_V(n) asm volatile("s_waitcnt vmcnt(" #n ")" ::: "memory")
; #define PG8_WAIT_L(n) asm volatile("s_waitcnt lgkmcnt(" #n ")" ::: "memory")
; #define PG8_BAR __builtin_amdgcn_s_barrier()
; #define PG8_SCHED __builtin_amdgcn_sched_barrier(0)
; template <class Epi>
; __device__ __forceinline__ void gemm_phase(LAS unsigned char* lds, const Gemm g, const Sched& S, const Epi& E) {
;     ...
;             PG8_BAR; PG8_WAIT_L(0); PG8_MMA(0, 1, At, B1); PG8_BAR;
;             PG8_LDA(At, 0, 1); PG8_STAGE(PG8_SA(0, 0), a2, voffA);
;             PG8_BAR; PG8_WAIT_L(0); PG8_MMA(1, 0, At, B0); PG8_BAR; PG8_SCHED;
;             PG8_STAGE(PG8_SB(0, 1), b2 + hstepB, voffB);
;             PG8_WAIT_V(6); PG8_BAR; PG8_MMA(1, 1, At, B1); PG8_BAR;
;             PG8_LDB(B0, 1, 0); PG8_SCHED; PG8_LDA(At, 1, 0); PG8_STAGE(PG8_SA(0, 1), a2 + hstepA, voffA);
;             PG8_WAIT_L(8); PG8_BAR; PG8_WAIT_L(0); PG8_MMA(0, 0, At, B0); PG8_BAR; PG8_SCHED;
	s_setprio 1
	v_mfma_f32_16x16x32_bf16 v[62:65], v[144:147], v[184:187], v[62:65]
	v_mfma_f32_16x16x32_bf16 v[58:61], v[176:179], v[184:187], v[58:61]
	v_mfma_f32_16x16x32_bf16 v[50:53], v[144:147], v[196:199], v[50:53]
	v_mfma_f32_16x16x32_bf16 v[42:45], v[176:179], v[196:199], v[42:45]
	v_mfma_f32_16x16x32_bf16 v[34:37], v[144:147], v[204:207], v[34:37]
	v_mfma_f32_16x16x32_bf16 v[26:29], v[176:179], v[204:207], v[26:29]
	v_mfma_f32_16x16x32_bf16 v[18:21], v[144:147], v[212:215], v[18:21]
	v_mfma_f32_16x16x32_bf16 v[10:13], v[176:179], v[212:215], v[10:13]
	v_mfma_f32_16x16x32_bf16 v[62:65], v[172:175], v[188:191], v[62:65]
	v_mfma_f32_16x16x32_bf16 v[58:61], v[180:183], v[188:191], v[58:61]
	v_mfma_f32_16x16x32_bf16 v[50:53], v[172:175], v[200:203], v[50:53]
	v_mfma_f32_16x16x32_bf16 v[42:45], v[180:183], v[200:203], v[42:45]
	v_mfma_f32_16x16x32_bf16 v[34:37], v[172:175], v[208:211], v[34:37]
	v_mfma_f32_16x16x32_bf16 v[26:29], v[180:183], v[208:211], v[26:29]
	v_mfma_f32_16x16x32_bf16 v[18:21], v[172:175], v[222:225], v[18:21]
	v_mfma_f32_16x16x32_bf16 v[10:13], v[180:183], v[222:225], v[10:13]
	v_mfma_f32_16x16x32_bf16 v[54:57], v[226:229], v[184:187], v[54:57]
	v_mfma_f32_16x16x32_bf16 v[46:49], v[234:237], v[184:187], v[46:49]
	v_mfma_f32_16x16x32_bf16 v[38:41], v[226:229], v[196:199], v[38:41]
	v_mfma_f32_16x16x32_bf16 v[30:33], v[234:237], v[196:199], v[30:33]
	v_mfma_f32_16x16x32_bf16 v[22:25], v[226:229], v[204:207], v[22:25]
	v_mfma_f32_16x16x32_bf16 v[14:17], v[234:237], v[204:207], v[14:17]
	v_mfma_f32_16x16x32_bf16 v[6:9], v[226:229], v[212:215], v[6:9]
	v_mfma_f32_16x16x32_bf16 v[2:5], v[234:237], v[212:215], v[2:5]
	v_mfma_f32_16x16x32_bf16 v[54:57], v[230:233], v[188:191], v[54:57]
	v_mfma_f32_16x16x32_bf16 v[46:49], v[238:241], v[188:191], v[46:49]
	v_mfma_f32_16x16x32_bf16 v[38:41], v[230:233], v[200:203], v[38:41]
	v_mfma_f32_16x16x32_bf16 v[30:33], v[238:241], v[200:203], v[30:33]
	v_mfma_f32_16x16x32_bf16 v[22:25], v[230:233], v[208:211], v[22:25]
	v_mfma_f32_16x16x32_bf16 v[14:17], v[238:241], v[208:211], v[14:17]
	v_mfma_f32_16x16x32_bf16 v[6:9], v[230:233], v[222:225], v[6:9]
	v_mfma_f32_16x16x32_bf16 v[2:5], v[238:241], v[222:225], v[2:5]
	s_setprio 0
	s_barrier
	s_add_i32 s8, 0, 0x18000
	v_add_u32_e32 v180, s8, v152
	ds_read_b128 v[144:147], v180
	ds_read_b128 v[172:175], v180 offset:1024
	ds_read_b128 v[176:179], v180 offset:2048
	ds_read_b128 v[180:183], v180 offset:3072
	s_add_u32 s94, s94, s4
	s_addc_u32 s95, s95, s5
	s_mov_b32 m0, s52
	v_lshl_add_u64 v[226:227], s[94:95], 0, v[130:131]
	ds_read_b128 v[184:187], v171 offset:32768
	ds_read_b128 v[188:191], v171 offset:33792
	ds_read_b128 v[196:199], v171 offset:34816
	ds_read_b128 v[200:203], v171 offset:35840
	ds_read_b128 v[204:207], v171 offset:36864
	ds_read_b128 v[208:211], v171 offset:37888
	ds_read_b128 v[212:215], v171 offset:38912
	ds_read_b128 v[222:225], v171 offset:39936
	global_load_lds_dwordx4 v[226:227], off
	v_lshl_add_u64 v[226:227], s[94:95], 0, v[134:135]
	s_mov_b32 m0, s53
	s_nop 0
	global_load_lds_dwordx4 v[226:227], off
	s_add_i32 s9, 0, 0x1c000
	v_add_u32_e32 v218, s9, v152
	ds_read_b128 v[226:229], v218
	ds_read_b128 v[230:233], v218 offset:1024
	ds_read_b128 v[234:237], v218 offset:2048
	ds_read_b128 v[238:241], v218 offset:3072
	s_waitcnt vmcnt(8)
	s_waitcnt lgkmcnt(0)
	s_barrier
	s_setprio 1
	v_mfma_f32_16x16x32_bf16 v[126:129], v[144:147], v[184:187], v[126:129]
	v_mfma_f32_16x16x32_bf16 v[122:125], v[176:179], v[184:187], v[122:125]
	v_mfma_f32_16x16x32_bf16 v[110:113], v[144:147], v[196:199], v[110:113]
	v_mfma_f32_16x16x32_bf16 v[106:109], v[176:179], v[196:199], v[106:109]
	v_mfma_f32_16x16x32_bf16 v[94:97], v[144:147], v[204:207], v[94:97]
	v_mfma_f32_16x16x32_bf16 v[90:93], v[176:179], v[204:207], v[90:93]
	v_mfma_f32_16x16x32_bf16 v[78:81], v[144:147], v[212:215], v[78:81]
	v_mfma_f32_16x16x32_bf16 v[74:77], v[176:179], v[212:215], v[74:77]
	v_mfma_f32_16x16x32_bf16 v[126:129], v[172:175], v[188:191], v[126:129]
	v_mfma_f32_16x16x32_bf16 v[122:125], v[180:183], v[188:191], v[122:125]
	v_mfma_f32_16x16x32_bf16 v[110:113], v[172:175], v[200:203], v[110:113]
	v_mfma_f32_16x16x32_bf16 v[106:109], v[180:183], v[200:203], v[106:109]
	v_mfma_f32_16x16x32_bf16 v[94:97], v[172:175], v[208:211], v[94:97]
	v_mfma_f32_16x16x32_bf16 v[90:93], v[180:183], v[208:211], v[90:93]
	v_mfma_f32_16x16x32_bf16 v[78:81], v[172:175], v[222:225], v[78:81]
	v_mfma_f32_16x16x32_bf16 v[74:77], v[180:183], v[222:225], v[74:77]
	v_mfma_f32_16x16x32_bf16 v[118:121], v[226:229], v[184:187], v[118:121]
	v_mfma_f32_16x16x32_bf16 v[114:117], v[234:237], v[184:187], v[114:117]
	v_mfma_f32_16x16x32_bf16 v[102:105], v[226:229], v[196:199], v[102:105]
	v_mfma_f32_16x16x32_bf16 v[98:101], v[234:237], v[196:199], v[98:101]
	v_mfma_f32_16x16x32_bf16 v[86:89], v[226:229], v[204:207], v[86:89]
	v_mfma_f32_16x16x32_bf16 v[82:85], v[234:237], v[204:207], v[82:85]
	v_mfma_f32_16x16x32_bf16 v[70:73], v[226:229], v[212:215], v[70:73]
	v_mfma_f32_16x16x32_bf16 v[66:69], v[234:237], v[212:215], v[66:69]
	v_mfma_f32_16x16x32_bf16 v[118:121], v[230:233], v[188:191], v[118:121]
	v_mfma_f32_16x16x32_bf16 v[114:117], v[238:241], v[188:191], v[114:117]
	v_mfma_f32_16x16x32_bf16 v[102:105], v[230:233], v[200:203], v[102:105]
	v_mfma_f32_16x16x32_bf16 v[98:101], v[238:241], v[200:203], v[98:101]
	v_mfma_f32_16x16x32_bf16 v[86:89], v[230:233], v[208:211], v[86:89]
	v_mfma_f32_16x16x32_bf16 v[82:85], v[238:241], v[208:211], v[82:85]
	v_mfma_f32_16x16x32_bf16 v[70:73], v[230:233], v[222:225], v[70:73]
	v_mfma_f32_16x16x32_bf16 v[66:69], v[238:241], v[222:225], v[66:69]
	s_setprio 0
	s_barrier
; #define PG8_STAGE(bufoff, gbase, voff) do { _Pragma("unroll") for (int _i = 0; _i < 2; ++_i) \
;         __builtin_amdgcn_global_load_lds((const unsigned*)((const char*)(gbase) + (voff)[_i]), (LAS unsigned*)(lds + (bufoff) + ldsw + _i * 8192), 16, 0, 0); } while (0)
; #define PG8_LDA(dst, b, h) do { _Pragma("unroll") for (int m = 0; m < 4; ++m) _Pragma("unroll") for (int k = 0; k < 2; ++k) dst[m][k] = *(const LAS bf16x8*)(lds + PG8_SA(b, h) + aoff + m * 2048 + k * 1024); } while (0)
; #define PG8_LDB(dst, b, h) do { _Pragma("unroll") for (int n = 0; n < 2; ++n) _Pragma("unroll") for (int k = 0; k < 2; ++k) dst[n][k] = *(const LAS bf16x8*)(lds + PG8_SB(b, h) + boff + n * 2048 + k * 1024); } while (0)
; #define PG8_WAIT_V(n) asm volatile("s_waitcnt vmcnt(" #n ")" ::: "memory")
; #define PG8_WAIT_L(n) asm volatile("s_waitcnt lgkmcnt(" #n ")" ::: "memory")
; #define PG8_BAR __builtin_amdgcn_s_barrier()
; #define PG8_SCHED __builtin_amdgcn_sched_barrier(0)
; template <class Epi>
; __device__ __forceinline__ void gemm_phase(LAS unsigned char* lds, const Gemm g, const Sched& S, const Epi& E) {
;     ...
;             PG8_LDB(B0, 1, 0); PG8_SCHED; PG8_LDA(At, 1, 0); PG8_STAGE(PG8_SA(0, 1), a2 + hstepA, voffA);
;             PG8_WAIT_L(8); PG8_BAR; PG8_WAIT_L(0); PG8_MMA(0, 0, At, B0); PG8_BAR; PG8_SCHED;
;             PG8_LDB(B1, 1, 1); PG8_STAGE(PG8_SB(1, 0), b3, voffB);
;             PG8_BAR; PG8_WAIT_L(0); PG8_MMA(0, 1, At, B1); PG8_BAR;
;             PG8_LDA(At, 1, 1); PG8_STAGE(PG8_SA(1, 0), a3, voffA);
;             PG8_BAR; PG8_WAIT_L(0); PG8_MMA(1, 0, At, B0); PG8_BAR; PG8_SCHED;
;             PG8_STAGE(PG8_SB(1, 1), b3 + hstepB, voffB);
;             PG8_WAIT_V(6); PG8_BAR; PG8_MMA(1, 1, At, B1); PG8_BAR;
;         }
;     __device__ __forceinline__ void operator()(const Acc& acc, const Unit& u, int wr, int wc, int fr, int fq, const Pre& pre) const {
;     ...
;             for (int m = 0; m < 4; ++m) { float mx = -INFINITY;
; #pragma unroll
;                 for (int bj = 0; bj < 2; ++bj)
; #pragma unroll
;                     for (int n = 0; n < 2; ++n) { const f32x4 a = acc[ai][bj][m][n]; mx = fmaxf(mx, fmaxf(fmaxf(a[0], a[1]), fmaxf(a[2], a[3]))); }
;                 mx *= rs[ai][m];
;                 mx = fmaxf(mx, __shfl_xor(mx, 16)); mx = fmaxf(mx, __shfl_xor(mx, 32));
;                 if (fq == 0) X[(ai * 128 + wr * 64 + m * 16 + fr) * 4 + wc] = mx; }
	s_add_i32 s8, s8, s39
	v_lshl_add_u64 v[148:149], v[148:149], 0, s[60:61]
	s_mov_b32 m0, s8
	s_nop 0
	global_load_lds_dwordx4 v[148:149], off
	v_lshl_add_u64 v[148:149], v[192:193], 0, s[60:61]
	s_add_i32 m0, s8, 0x2000
	s_nop 0
	global_load_lds_dwordx4 v[148:149], off
	s_mov_b32 m0, s67
	v_lshl_add_u64 v[148:149], v[194:195], 0, s[60:61]
	ds_read_b128 v[184:187], v171 offset:49152
	ds_read_b128 v[188:191], v171 offset:50176
	ds_read_b128 v[196:199], v171 offset:51200
	ds_read_b128 v[200:203], v171 offset:52224
	ds_read_b128 v[204:207], v171 offset:53248
	ds_read_b128 v[208:211], v171 offset:54272
	ds_read_b128 v[212:215], v171 offset:55296
	ds_read_b128 v[222:225], v171 offset:56320
	global_load_lds_dwordx4 v[148:149], off
	v_lshl_add_u64 v[148:149], v[216:217], 0, s[60:61]
	s_mov_b32 m0, s2
	s_nop 0
	global_load_lds_dwordx4 v[148:149], off
	s_add_i32 s8, s9, s39
	v_lshl_add_u64 v[148:149], v[242:243], 0, s[60:61]
	s_mov_b32 m0, s8
	s_nop 0
	global_load_lds_dwordx4 v[148:149], off
	v_lshl_add_u64 v[148:149], v[244:245], 0, s[60:61]
	s_add_i32 m0, s8, 0x2000
	s_nop 0
	global_load_lds_dwordx4 v[148:149], off
	s_waitcnt vmcnt(8)
	s_waitcnt lgkmcnt(0)
	s_barrier
	s_setprio 1
	v_mfma_f32_16x16x32_bf16 v[62:65], v[144:147], v[184:187], v[62:65]
	v_mfma_f32_16x16x32_bf16 v[58:61], v[176:179], v[184:187], v[58:61]
	v_mfma_f32_16x16x32_bf16 v[50:53], v[144:147], v[196:199], v[50:53]
	v_mfma_f32_16x16x32_bf16 v[42:45], v[176:179], v[196:199], v[42:45]
	v_mfma_f32_16x16x32_bf16 v[34:37], v[144:147], v[204:207], v[34:37]
	v_mfma_f32_16x16x32_bf16 v[26:29], v[176:179], v[204:207], v[26:29]
	v_mfma_f32_16x16x32_bf16 v[18:21], v[144:147], v[212:215], v[18:21]
	v_mfma_f32_16x16x32_bf16 v[10:13], v[176:179], v[212:215], v[10:13]
	v_mfma_f32_16x16x32_bf16 v[62:65], v[172:175], v[188:191], v[62:65]
	v_mfma_f32_16x16x32_bf16 v[58:61], v[180:183], v[188:191], v[58:61]
	v_mfma_f32_16x16x32_bf16 v[50:53], v[172:175], v[200:203], v[50:53]
	v_mfma_f32_16x16x32_bf16 v[42:45], v[180:183], v[200:203], v[42:45]
	v_mfma_f32_16x16x32_bf16 v[34:37], v[172:175], v[208:211], v[34:37]
	v_mfma_f32_16x16x32_bf16 v[26:29], v[180:183], v[208:211], v[26:29]
	v_mfma_f32_16x16x32_bf16 v[18:21], v[172:175], v[222:225], v[18:21]
	v_mfma_f32_16x16x32_bf16 v[10:13], v[180:183], v[222:225], v[10:13]
	v_mfma_f32_16x16x32_bf16 v[54:57], v[226:229], v[184:187], v[54:57]
	v_mfma_f32_16x16x32_bf16 v[46:49], v[234:237], v[184:187], v[46:49]
	v_mfma_f32_16x16x32_bf16 v[38:41], v[226:229], v[196:199], v[38:41]
	v_mfma_f32_16x16x32_bf16 v[30:33], v[234:237], v[196:199], v[30:33]
	v_mfma_f32_16x16x32_bf16 v[22:25], v[226:229], v[204:207], v[22:25]
	v_mfma_f32_16x16x32_bf16 v[14:17], v[234:237], v[204:207], v[14:17]
	v_mfma_f32_16x16x32_bf16 v[6:9], v[226:229], v[212:215], v[6:9]
	v_mfma_f32_16x16x32_bf16 v[2:5], v[234:237], v[212:215], v[2:5]
	v_mfma_f32_16x16x32_bf16 v[54:57], v[230:233], v[188:191], v[54:57]
	v_mfma_f32_16x16x32_bf16 v[46:49], v[238:241], v[188:191], v[46:49]
	v_mfma_f32_16x16x32_bf16 v[38:41], v[230:233], v[200:203], v[38:41]
	v_mfma_f32_16x16x32_bf16 v[30:33], v[238:241], v[200:203], v[30:33]
	v_mfma_f32_16x16x32_bf16 v[22:25], v[230:233], v[208:211], v[22:25]
	v_mfma_f32_16x16x32_bf16 v[14:17], v[238:241], v[208:211], v[14:17]
	v_mfma_f32_16x16x32_bf16 v[6:9], v[230:233], v[222:225], v[6:9]
	v_mfma_f32_16x16x32_bf16 v[2:5], v[238:241], v[222:225], v[2:5]
	s_setprio 0
	s_add_u32 s92, s92, 0x100
	s_addc_u32 s93, s93, 0
	s_add_u32 s34, s34, 0x100
	s_addc_u32 s35, s35, 0
	s_cmp_ge_u32 s14, s73
	s_mov_b32 s66, s14
	s_barrier
	s_cbranch_scc0 .LBB0_400
	v_and_b32_e32 v144, 64, v220
	v_or_b32_e32 v144, v144, v150
	v_lshlrev_b32_e32 v172, 2, v144
	ds_bpermute_b32 v145, v172, v143
	ds_bpermute_b32 v144, v172, v143 offset:64
	s_mov_b32 s8, 0x3a000000
	v_mov_b32_e32 v232, 0x358637bd
	s_mov_b32 s97, 0x800000
	ds_bpermute_b32 v147, v172, v143 offset:128
	s_waitcnt lgkmcnt(0)
	v_pk_fma_f32 v[148:149], v[144:145], s[8:9], v[232:233] op_sel_hi:[1,0,0]
	ds_bpermute_b32 v146, v172, v143 offset:192
	v_mul_f32_e32 v143, 0x4b800000, v149
	v_cmp_gt_f32_e32 vcc, s97, v149
	v_max_f32_e32 v174, v128, v128
	v_max_f32_e32 v175, v124, v124
	v_cndmask_b32_e32 v143, v149, v143, vcc
	v_rsq_f32_e32 v149, v143
	v_max_f32_e32 v176, v116, v116
	ds_bpermute_b32 v145, v172, v142
	ds_bpermute_b32 v144, v172, v142 offset:64
	v_mul_f32_e32 v173, 0x45800000, v149
	v_cndmask_b32_e32 v149, v149, v173, vcc
	v_max_f32_e32 v173, v129, v129
	v_max_f32_e32 v173, v174, v173
	v_max_f32_e32 v174, v125, v125
	v_max_f32_e32 v174, v175, v174
	v_max3_f32 v173, v126, v127, v173
	v_max3_f32 v174, v122, v123, v174
	v_max3_f32 v173, v173, s72, v174
	v_max_f32_e32 v174, v121, v121
	v_max_f32_e32 v175, v120, v120
	v_max_f32_e32 v174, v175, v174
	v_max_f32_e32 v175, v117, v117
	v_max_f32_e32 v175, v176, v175
	v_cmp_lt_i32_e32 vcc, v221, v247
	v_max3_f32 v174, v118, v119, v174
	v_max3_f32 v175, v114, v115, v175
	v_cndmask_b32_e64 v177, v149, 1.0, s[80:81]
	v_cndmask_b32_e32 v149, v220, v221, vcc
	v_max3_f32 v173, v173, v174, v175
	v_lshlrev_b32_e32 v149, 2, v149
	v_mul_f32_e32 v173, v173, v177
	ds_bpermute_b32 v174, v149, v173
	v_cmp_lt_i32_e32 vcc, v248, v247
	ds_bpermute_b32 v143, v172, v142 offset:128
	ds_bpermute_b32 v142, v172, v142 offset:192
	v_cndmask_b32_e32 v172, v220, v248, vcc
	s_waitcnt lgkmcnt(0)
	v_max_f32_e32 v174, v174, v174
	v_lshlrev_b32_e32 v172, 2, v172
	v_max_f32_e32 v173, v173, v174
	ds_bpermute_b32 v174, v172, v173
	v_cmp_gt_f32_e32 vcc, s97, v148
	v_add_u32_e32 v178, s51, v154
	s_and_saveexec_b64 s[92:93], s[0:1]
	s_cbranch_execz .LBB0_403
	s_waitcnt lgkmcnt(0)
	v_max_f32_e32 v174, v174, v174
	v_max_f32_e32 v173, v173, v173
	v_max_f32_e32 v173, v173, v174
	ds_write_b32 v178, v173

; __device__ __forceinline__ int otid() { int t = threadIdx.x; asm volatile("" : "+v"(t)); return t; }
; #define PG8_STAGE(bufoff, gbase, voff) do { _Pragma("unroll") for (int _i = 0; _i < 2; ++_i) \
;         __builtin_amdgcn_global_load_lds((const unsigned*)((const char*)(gbase) + (voff)[_i]), (LAS unsigned*)(lds + (bufoff) + ldsw + _i * 8192), 16, 0, 0); } while (0)
; #define PG8_WAIT_V(n) asm volatile("s_waitcnt vmcnt(" #n ")" ::: "memory")
; #define PG8_BAR __builtin_amdgcn_s_barrier()
;     __device__ __forceinline__ Pre prefetch(const Unit& u, int wr, int fr) const { return pre_rows(ss, u.pm * 256 + wr * 64 + (int)(threadIdx.x & 63)); }
;     __device__ __forceinline__ Pre prefetch(const Unit& u, int wr, int fr) const { return pre_rows(ss, u.pm * 256 + wr * 64 + (int)(threadIdx.x & 63)); }
; template <class Epi>
; __device__ __forceinline__ void gemm_phase(LAS unsigned char* lds, const Gemm g, const Sched& S, const Epi& E) {
;     const int tid = otid(), wid = __builtin_amdgcn_readfirstlane(tid >> 6), lane = tid & 63, wr = wid >> 2, wc = wid & 3, fr = lane & 15, fq = lane >> 4;
;     const int nt = g.K / BK;
;     unsigned voffA[2], voffB[2];
; #pragma unroll
;     for (int i = 0; i < 2; ++i) { int R, C; stage_rc(tid * 16 + i * 8192, R, C); const int Rb = Epi::PERM ? ((R & ~31) + perm32(R & 31)) : R;
;         voffA[i] = (unsigned)(R * g.lda + C) * 2u; voffB[i] = (unsigned)(Rb * g.ldb + C) * 2u; }
;     const size_t kstep = (size_t)(BK * 2);
;     const size_t hstepA = (size_t)HALF * g.lda * 2, hstepB = (size_t)HALF * g.ldb * 2;
;     const unsigned ldsw = (unsigned)wid * 1024u;
;     const int aoff = lds_byte(wr * 64 + fr, fq * 8), boff = lds_byte(wc * 32 + fr, fq * 8);
;     ...
;     PG8_STAGE(PG8_SB(0, 0), cB, voffB); PG8_STAGE(PG8_SA(0, 0), cA, voffA); PG8_STAGE(PG8_SB(0, 1), cB + hstepB, voffB); PG8_STAGE(PG8_SA(0, 1), cA + hstepA, voffA);
;     if (wr == 1) PG8_BAR;
;     PG8_WAIT_V(4); PG8_BAR;
;     PG8_STAGE(PG8_SB(1, 0), cB + kstep, voffB); PG8_STAGE(PG8_SA(1, 0), cA + kstep, voffA); PG8_STAGE(PG8_SB(1, 1), cB + hstepB + kstep, voffB);
;     PG8_WAIT_V(6); PG8_BAR;
;     for (;;) {
;         const Pre pre = E.prefetch(cur, wr, fr);
;         const bool has_next = S.next(ui + 1, nxt);
;         const char* nA = has_next ? (const char*)g.A + nxt.ao : cA; const char* nB = has_next ? (const char*)g.Bt + nxt.bo : cB;
.LBB0_449:
	s_add_i32 m0, s24, 0x18000
	v_lshl_add_u64 v[2:3], v[2:3], 0, s[60:61]
	s_waitcnt vmcnt(0)
	s_barrier
	global_load_lds_dwordx4 v[2:3], off
	v_lshl_add_u64 v[2:3], v[4:5], 0, s[60:61]
	s_add_i32 m0, s24, 0x1a000
	s_add_i32 s40, s24, 0x8000
	global_load_lds_dwordx4 v[2:3], off
	v_lshl_add_u64 v[2:3], v[6:7], 0, s[60:61]
	s_mov_b32 m0, s40
	s_add_i32 s41, s24, 0xa000
	global_load_lds_dwordx4 v[2:3], off
	v_lshl_add_u64 v[2:3], v[8:9], 0, s[60:61]
	s_mov_b32 m0, s41
	v_lshrrev_b32_e32 v22, 1, v15
	global_load_lds_dwordx4 v[2:3], off
	s_add_i32 m0, s24, 0x1c000
	v_lshl_add_u64 v[2:3], v[10:11], 0, s[60:61]
	global_load_lds_dwordx4 v[2:3], off
	v_lshl_add_u64 v[2:3], v[12:13], 0, s[60:61]
	s_add_i32 m0, s24, 0x1e000
	v_and_b32_e32 v22, 24, v22
	global_load_lds_dwordx4 v[2:3], off
	v_and_b32_e32 v21, 15, v15
	v_lshlrev_b32_e32 v23, 1, v22
	v_lshlrev_b32_e32 v15, 2, v15
	s_lshl_b32 s0, s0, 5
	v_lshl_or_b32 v210, s1, 6, v21
	v_lshl_or_b32 v21, v21, 6, v23
	s_lshl_b32 s1, s1, 13
	v_and_b32_e32 v15, 32, v15
	s_and_b32 s0, s0, 0x60
	v_bitop3_b32 v23, v21, s1, v15 bitop3:0xde
	s_lshl_b32 s1, s0, 7
	v_bitop3_b32 v211, v21, s1, v15 bitop3:0xde
	v_readlane_b32 s1, v254, 13
	v_readlane_b32 s8, v253, 30
	s_ashr_i32 s43, s1, 31
	v_readlane_b32 s1, v254, 5
	v_readlane_b32 s8, v254, 37
	s_mul_i32 s53, s1, s8
	v_cvt_f32_u32_e32 v2, s53
	v_or_b32_e32 v212, s0, v22
	s_sub_i32 s0, 0, s53
	v_mov_b32_e32 v3, v1
	v_rcp_iflag_f32_e32 v2, v2
	s_waitcnt vmcnt(6)
	v_readlane_b32 s9, v253, 31
	s_lshr_b32 s48, s54, 3
	v_mul_f32_e32 v2, 0x4f7ffffe, v2
	v_cvt_u32_f32_e32 v2, v2
	s_add_i32 s42, s73, -2
	s_mov_b32 s27, s9
	s_and_b32 s51, s54, 7
	v_readfirstlane_b32 s1, v2
	v_cvt_f32_u32_e32 v2, s25
	s_mul_i32 s0, s0, s1
	s_mul_hi_u32 s0, s1, s0
	s_add_i32 s58, s1, s0
	v_rcp_iflag_f32_e32 v2, v2
	s_sub_i32 s0, 0, s25
	s_add_i32 s52, s48, 1
	s_mov_b32 s56, 0
	v_mul_f32_e32 v2, 0x4f7ffffe, v2
	v_cvt_u32_f32_e32 v2, v2
	v_add_u32_e32 v213, 0, v23
	s_barrier
	v_readfirstlane_b32 s1, v2
	v_add_u32_e32 v2, v17, v14
	v_add_lshl_u32 v2, v2, v16, 1
	s_mul_i32 s0, s0, s1
	v_lshl_add_u64 v[202:203], s[36:37], 0, v[2:3]
	v_add_u32_e32 v2, v20, v18
	s_mul_hi_u32 s0, s1, s0
	v_add_lshl_u32 v2, v2, v19, 1
	s_add_i32 s64, s1, s0
	v_lshl_add_u64 v[204:205], s[36:37], 0, v[2:3]
	s_branch .LBB0_451

; #define PG8_STAGE(bufoff, gbase, voff) do { _Pragma("unroll") for (int _i = 0; _i < 2; ++_i) \
;         __builtin_amdgcn_global_load_lds((const unsigned*)((const char*)(gbase) + (voff)[_i]), (LAS unsigned*)(lds + (bufoff) + ldsw + _i * 8192), 16, 0, 0); } while (0)
; #define PG8_LDA(dst, b, h) do { _Pragma("unroll") for (int m = 0; m < 4; ++m) _Pragma("unroll") for (int k = 0; k < 2; ++k) dst[m][k] = *(const LAS bf16x8*)(lds + PG8_SA(b, h) + aoff + m * 2048 + k * 1024); } while (0)
; #define PG8_LDB(dst, b, h) do { _Pragma("unroll") for (int n = 0; n < 2; ++n) _Pragma("unroll") for (int k = 0; k < 2; ++k) dst[n][k] = *(const LAS bf16x8*)(lds + PG8_SB(b, h) + boff + n * 2048 + k * 1024); } while (0)
; #define PG8_MMA(ai, bj, At, Bt) do { __builtin_amdgcn_s_setprio(1); _Pragma("unroll") for (int m = 0; m < 4; ++m) _Pragma("unroll") for (int n = 0; n < 2; ++n) _Pragma("unroll") for (int k = 0; k < 2; ++k) \
;         acc[ai][bj][m][n] = __builtin_amdgcn_mfma_f32_16x16x32_bf16(Bt[n][k], At[m][k], acc[ai][bj][m][n], 0, 0, 0); __builtin_amdgcn_s_setprio(0); } while (0)
; #define PG8_WAIT_L(n) asm volatile("s_waitcnt lgkmcnt(" #n ")" ::: "memory")
; #define PG8_BAR __builtin_amdgcn_s_barrier()
; #define PG8_SCHED __builtin_amdgcn_sched_barrier(0)
; template <class Epi>
; __device__ __forceinline__ void gemm_phase(LAS unsigned char* lds, const Gemm g, const Sched& S, const Epi& E) {
;     ...
;         for (int t = 0; t < nt; t += 2) {
;             const bool last = (t == nt - 2);
;             const char* a1 = cA + (size_t)(t + 1) * kstep;
;             const char* a2 = last ? nA : cA + (size_t)(t + 2) * kstep; const char* b2 = last ? nB : cB + (size_t)(t + 2) * kstep;
;             const char* a3 = a2 + kstep; const char* b3 = b2 + kstep;
;             PG8_LDB(B0, 0, 0); PG8_SCHED; PG8_LDA(At, 0, 0); PG8_STAGE(PG8_SA(1, 1), a1 + hstepA, voffA);
;             PG8_WAIT_L(8); PG8_BAR; PG8_WAIT_L(0); PG8_MMA(0, 0, At, B0); PG8_BAR; PG8_SCHED;
;             PG8_LDB(B1, 0, 1); PG8_STAGE(PG8_SB(0, 0), b2, voffB);
;             PG8_BAR; PG8_WAIT_L(0); PG8_MMA(0, 1, At, B1); PG8_BAR;
;             PG8_LDA(At, 0, 1); PG8_STAGE(PG8_SA(0, 0), a2, voffA);
.LBB0_461:
	s_add_i32 s14, s88, 2
	s_add_u32 s8, s4, 0x80
	s_addc_u32 s9, s5, 0
	s_add_i32 s15, 0, 0x10000
	v_add_u32_e32 v114, s15, v211
	ds_read_b128 v[82:85], v114
	ds_read_b128 v[94:97], v114 offset:1024
	ds_read_b128 v[98:101], v114 offset:2048
	ds_read_b128 v[114:117], v114 offset:3072
	s_cmp_eq_u32 s42, s88
	s_cselect_b32 s88, s57, s8
	s_cselect_b32 s89, s71, s9
	s_cselect_b32 s91, s59, s35
	s_cselect_b32 s90, s72, s34
	v_lshl_add_u64 v[178:179], s[4:5], 0, v[202:203]
	s_add_i32 m0, s24, 0xc000
	ds_read_b128 v[122:125], v213
	ds_read_b128 v[130:133], v213 offset:1024
	ds_read_b128 v[146:149], v213 offset:2048
	ds_read_b128 v[150:153], v213 offset:3072
	ds_read_b128 v[162:165], v213 offset:4096
	ds_read_b128 v[166:169], v213 offset:5120
	ds_read_b128 v[170:173], v213 offset:6144
	ds_read_b128 v[174:177], v213 offset:7168
	global_load_lds_dwordx4 v[178:179], off
	v_lshl_add_u64 v[178:179], s[4:5], 0, v[204:205]
	s_add_i32 m0, s24, 0xe000
	s_nop 0
	global_load_lds_dwordx4 v[178:179], off
	s_add_i32 s8, 0, 0x14000
	v_add_u32_e32 v190, s8, v211
	ds_read_b128 v[178:181], v190
	ds_read_b128 v[182:185], v190 offset:1024
	ds_read_b128 v[186:189], v190 offset:2048
	ds_read_b128 v[190:193], v190 offset:3072
	s_waitcnt vmcnt(8)
	s_waitcnt lgkmcnt(0)
	s_barrier
	s_setprio 1
	v_mfma_f32_16x16x32_bf16 v[158:161], v[82:85], v[122:125], v[158:161]
	v_mfma_f32_16x16x32_bf16 v[154:157], v[98:101], v[122:125], v[154:157]
	v_mfma_f32_16x16x32_bf16 v[134:137], v[82:85], v[146:149], v[134:137]
	v_mfma_f32_16x16x32_bf16 v[126:129], v[98:101], v[146:149], v[126:129]
	v_mfma_f32_16x16x32_bf16 v[106:109], v[82:85], v[162:165], v[106:109]
	v_mfma_f32_16x16x32_bf16 v[102:105], v[98:101], v[162:165], v[102:105]
	v_mfma_f32_16x16x32_bf16 v[78:81], v[82:85], v[170:173], v[78:81]
	v_mfma_f32_16x16x32_bf16 v[74:77], v[98:101], v[170:173], v[74:77]
	v_mfma_f32_16x16x32_bf16 v[158:161], v[94:97], v[130:133], v[158:161]
	v_mfma_f32_16x16x32_bf16 v[154:157], v[114:117], v[130:133], v[154:157]
	v_mfma_f32_16x16x32_bf16 v[134:137], v[94:97], v[150:153], v[134:137]
	v_mfma_f32_16x16x32_bf16 v[126:129], v[114:117], v[150:153], v[126:129]
	v_mfma_f32_16x16x32_bf16 v[106:109], v[94:97], v[166:169], v[106:109]
	v_mfma_f32_16x16x32_bf16 v[102:105], v[114:117], v[166:169], v[102:105]
	v_mfma_f32_16x16x32_bf16 v[78:81], v[94:97], v[174:177], v[78:81]
	v_mfma_f32_16x16x32_bf16 v[74:77], v[114:117], v[174:177], v[74:77]
	v_mfma_f32_16x16x32_bf16 v[142:145], v[178:181], v[122:125], v[142:145]
	v_mfma_f32_16x16x32_bf16 v[118:121], v[178:181], v[146:149], v[118:121]
	v_mfma_f32_16x16x32_bf16 v[110:113], v[186:189], v[146:149], v[110:113]
	v_mfma_f32_16x16x32_bf16 v[90:93], v[178:181], v[162:165], v[90:93]
	v_mfma_f32_16x16x32_bf16 v[86:89], v[186:189], v[162:165], v[86:89]
	v_mfma_f32_16x16x32_bf16 v[70:73], v[178:181], v[170:173], v[70:73]
	v_mfma_f32_16x16x32_bf16 v[66:69], v[186:189], v[170:173], v[66:69]
	v_mfma_f32_16x16x32_bf16 v[142:145], v[182:185], v[130:133], v[142:145]
	v_mfma_f32_16x16x32_bf16 v[122:125], v[186:189], v[122:125], v[138:141]
	v_mfma_f32_16x16x32_bf16 v[118:121], v[182:185], v[150:153], v[118:121]
	v_mfma_f32_16x16x32_bf16 v[110:113], v[190:193], v[150:153], v[110:113]
	v_mfma_f32_16x16x32_bf16 v[90:93], v[182:185], v[166:169], v[90:93]
	v_mfma_f32_16x16x32_bf16 v[86:89], v[190:193], v[166:169], v[86:89]
	v_mfma_f32_16x16x32_bf16 v[70:73], v[182:185], v[174:177], v[70:73]
	v_mfma_f32_16x16x32_bf16 v[66:69], v[190:193], v[174:177], v[66:69]
	v_mfma_f32_16x16x32_bf16 v[122:125], v[190:193], v[130:133], v[122:125]
	s_setprio 0
	s_barrier
	s_add_i32 s9, s15, s3
	v_lshl_add_u64 v[194:195], s[90:91], 0, v[0:1]
	s_mov_b32 m0, s9
	s_nop 0
	global_load_lds_dwordx4 v[194:195], off
	v_lshl_add_u64 v[206:207], s[90:91], 0, v[200:201]
	s_add_i32 m0, s9, 0x2000
	s_nop 0
	global_load_lds_dwordx4 v[206:207], off
	s_mov_b32 m0, s24
	v_lshl_add_u64 v[208:209], s[88:89], 0, v[196:197]
	ds_read_b128 v[130:133], v213 offset:16384
	ds_read_b128 v[138:141], v213 offset:17408
	ds_read_b128 v[146:149], v213 offset:18432
	ds_read_b128 v[150:153], v213 offset:19456
	ds_read_b128 v[162:165], v213 offset:20480
	ds_read_b128 v[166:169], v213 offset:21504
	ds_read_b128 v[170:173], v213 offset:22528
	ds_read_b128 v[174:177], v213 offset:23552
	global_load_lds_dwordx4 v[208:209], off
	v_lshl_add_u64 v[214:215], s[88:89], 0, v[198:199]
	s_mov_b32 m0, s33
	s_nop 0
	global_load_lds_dwordx4 v[214:215], off
	s_add_u32 s90, s90, s78
	s_addc_u32 s91, s91, s79
	s_add_i32 s8, s8, s3
	v_lshl_add_u64 v[216:217], s[90:91], 0, v[0:1]
	s_mov_b32 m0, s8
	v_lshl_add_u64 v[222:223], s[90:91], 0, v[200:201]
	global_load_lds_dwordx4 v[216:217], off
	s_add_i32 m0, s8, 0x2000
	s_nop 0
	global_load_lds_dwordx4 v[222:223], off
	s_waitcnt vmcnt(8)
	s_waitcnt lgkmcnt(0)
	s_barrier
; #define PG8_STAGE(bufoff, gbase, voff) do { _Pragma("unroll") for (int _i = 0; _i < 2; ++_i) \
;         __builtin_amdgcn_global_load_lds((const unsigned*)((const char*)(gbase) + (voff)[_i]), (LAS unsigned*)(lds + (bufoff) + ldsw + _i * 8192), 16, 0, 0); } while (0)
; #define PG8_LDA(dst, b, h) do { _Pragma("unroll") for (int m = 0; m < 4; ++m) _Pragma("unroll") for (int k = 0; k < 2; ++k) dst[m][k] = *(const LAS bf16x8*)(lds + PG8_SA(b, h) + aoff + m * 2048 + k * 1024); } while (0)
; #define PG8_LDB(dst, b, h) do { _Pragma("unroll") for (int n = 0; n < 2; ++n) _Pragma("unroll") for (int k = 0; k < 2; ++k) dst[n][k] = *(const LAS bf16x8*)(lds + PG8_SB(b, h) + boff + n * 2048 + k * 1024); } while (0)
; #define PG8_MMA(ai, bj, At, Bt) do { __builtin_amdgcn_s_setprio(1); _Pragma("unroll") for (int m = 0; m < 4; ++m) _Pragma("unroll") for (int n = 0; n < 2; ++n) _Pragma("unroll") for (int k = 0; k < 2; ++k) \
;         acc[ai][bj][m][n] = __builtin_amdgcn_mfma_f32_16x16x32_bf16(Bt[n][k], At[m][k], acc[ai][bj][m][n], 0, 0, 0); __builtin_amdgcn_s_setprio(0); } while (0)
; #define PG8_WAIT_V(n) asm volatile("s_waitcnt vmcnt(" #n ")" ::: "memory")
; #define PG8_WAIT_L(n) asm volatile("s_waitcnt lgkmcnt(" #n ")" ::: "memory")
; #define PG8_BAR __builtin_amdgcn_s_barrier()
; #define PG8_SCHED __builtin_amdgcn_sched_barrier(0)
; template <class Epi>
; __device__ __forceinline__ void gemm_phase(LAS unsigned char* lds, const Gemm g, const Sched& S, const Epi& E) {
;     ...
;             PG8_BAR; PG8_WAIT_L(0); PG8_MMA(0, 1, At, B1); PG8_BAR;
;             PG8_LDA(At, 0, 1); PG8_STAGE(PG8_SA(0, 0), a2, voffA);
;             PG8_BAR; PG8_WAIT_L(0); PG8_MMA(1, 0, At, B0); PG8_BAR; PG8_SCHED;
;             PG8_STAGE(PG8_SB(0, 1), b2 + hstepB, voffB);
;             PG8_WAIT_V(6); PG8_BAR; PG8_MMA(1, 1, At, B1); PG8_BAR;
;             PG8_LDB(B0, 1, 0); PG8_SCHED; PG8_LDA(At, 1, 0); PG8_STAGE(PG8_SA(0, 1), a2 + hstepA, voffA);
;             PG8_WAIT_L(8); PG8_BAR; PG8_WAIT_L(0); PG8_MMA(0, 0, At, B0); PG8_BAR; PG8_SCHED;
	s_setprio 1
	v_mfma_f32_16x16x32_bf16 v[62:65], v[82:85], v[130:133], v[62:65]
	v_mfma_f32_16x16x32_bf16 v[58:61], v[98:101], v[130:133], v[58:61]
	v_mfma_f32_16x16x32_bf16 v[46:49], v[82:85], v[146:149], v[46:49]
	v_mfma_f32_16x16x32_bf16 v[42:45], v[98:101], v[146:149], v[42:45]
	v_mfma_f32_16x16x32_bf16 v[30:33], v[82:85], v[162:165], v[30:33]
	v_mfma_f32_16x16x32_bf16 v[26:29], v[98:101], v[162:165], v[26:29]
	v_mfma_f32_16x16x32_bf16 v[14:17], v[82:85], v[170:173], v[14:17]
	v_mfma_f32_16x16x32_bf16 v[10:13], v[98:101], v[170:173], v[10:13]
	v_mfma_f32_16x16x32_bf16 v[62:65], v[94:97], v[138:141], v[62:65]
	v_mfma_f32_16x16x32_bf16 v[58:61], v[114:117], v[138:141], v[58:61]
	v_mfma_f32_16x16x32_bf16 v[46:49], v[94:97], v[150:153], v[46:49]
	v_mfma_f32_16x16x32_bf16 v[42:45], v[114:117], v[150:153], v[42:45]
	v_mfma_f32_16x16x32_bf16 v[30:33], v[94:97], v[166:169], v[30:33]
	v_mfma_f32_16x16x32_bf16 v[26:29], v[114:117], v[166:169], v[26:29]
	v_mfma_f32_16x16x32_bf16 v[14:17], v[94:97], v[174:177], v[14:17]
	v_mfma_f32_16x16x32_bf16 v[10:13], v[114:117], v[174:177], v[10:13]
	v_mfma_f32_16x16x32_bf16 v[54:57], v[178:181], v[130:133], v[54:57]
	v_mfma_f32_16x16x32_bf16 v[50:53], v[186:189], v[130:133], v[50:53]
	v_mfma_f32_16x16x32_bf16 v[38:41], v[178:181], v[146:149], v[38:41]
	v_mfma_f32_16x16x32_bf16 v[34:37], v[186:189], v[146:149], v[34:37]
	v_mfma_f32_16x16x32_bf16 v[22:25], v[178:181], v[162:165], v[22:25]
	v_mfma_f32_16x16x32_bf16 v[18:21], v[186:189], v[162:165], v[18:21]
	v_mfma_f32_16x16x32_bf16 v[6:9], v[178:181], v[170:173], v[6:9]
	v_mfma_f32_16x16x32_bf16 v[2:5], v[186:189], v[170:173], v[2:5]
	v_mfma_f32_16x16x32_bf16 v[54:57], v[182:185], v[138:141], v[54:57]
	v_mfma_f32_16x16x32_bf16 v[50:53], v[190:193], v[138:141], v[50:53]
	v_mfma_f32_16x16x32_bf16 v[38:41], v[182:185], v[150:153], v[38:41]
	v_mfma_f32_16x16x32_bf16 v[34:37], v[190:193], v[150:153], v[34:37]
	v_mfma_f32_16x16x32_bf16 v[22:25], v[182:185], v[166:169], v[22:25]
	v_mfma_f32_16x16x32_bf16 v[18:21], v[190:193], v[166:169], v[18:21]
	v_mfma_f32_16x16x32_bf16 v[6:9], v[182:185], v[174:177], v[6:9]
	v_mfma_f32_16x16x32_bf16 v[2:5], v[190:193], v[174:177], v[2:5]
	s_setprio 0
	s_barrier
	s_add_i32 s8, 0, 0x18000
	v_add_u32_e32 v114, s8, v211
	ds_read_b128 v[82:85], v114
	ds_read_b128 v[94:97], v114 offset:1024
	ds_read_b128 v[98:101], v114 offset:2048
	ds_read_b128 v[114:117], v114 offset:3072
	s_add_u32 s88, s88, s36
	s_addc_u32 s89, s89, s37
	s_mov_b32 m0, s38
	v_lshl_add_u64 v[178:179], s[88:89], 0, v[196:197]
	ds_read_b128 v[130:133], v213 offset:32768
	ds_read_b128 v[138:141], v213 offset:33792
	ds_read_b128 v[146:149], v213 offset:34816
	ds_read_b128 v[150:153], v213 offset:35840
	ds_read_b128 v[162:165], v213 offset:36864
	ds_read_b128 v[166:169], v213 offset:37888
	ds_read_b128 v[170:173], v213 offset:38912
	ds_read_b128 v[174:177], v213 offset:39936
	global_load_lds_dwordx4 v[178:179], off
	v_lshl_add_u64 v[178:179], s[88:89], 0, v[198:199]
	s_mov_b32 m0, s39
	s_nop 0
	global_load_lds_dwordx4 v[178:179], off
	s_add_i32 s9, 0, 0x1c000
	v_add_u32_e32 v190, s9, v211
	ds_read_b128 v[178:181], v190
	ds_read_b128 v[182:185], v190 offset:1024
	ds_read_b128 v[186:189], v190 offset:2048
	ds_read_b128 v[190:193], v190 offset:3072
	s_waitcnt vmcnt(8)
	s_waitcnt lgkmcnt(0)
	s_barrier
	s_setprio 1
	v_mfma_f32_16x16x32_bf16 v[158:161], v[82:85], v[130:133], v[158:161]
	v_mfma_f32_16x16x32_bf16 v[154:157], v[98:101], v[130:133], v[154:157]
	v_mfma_f32_16x16x32_bf16 v[134:137], v[82:85], v[146:149], v[134:137]
	v_mfma_f32_16x16x32_bf16 v[126:129], v[98:101], v[146:149], v[126:129]
	v_mfma_f32_16x16x32_bf16 v[106:109], v[82:85], v[162:165], v[106:109]
	v_mfma_f32_16x16x32_bf16 v[102:105], v[98:101], v[162:165], v[102:105]
	v_mfma_f32_16x16x32_bf16 v[78:81], v[82:85], v[170:173], v[78:81]
	v_mfma_f32_16x16x32_bf16 v[74:77], v[98:101], v[170:173], v[74:77]
	v_mfma_f32_16x16x32_bf16 v[158:161], v[94:97], v[138:141], v[158:161]
	v_mfma_f32_16x16x32_bf16 v[154:157], v[114:117], v[138:141], v[154:157]
	v_mfma_f32_16x16x32_bf16 v[134:137], v[94:97], v[150:153], v[134:137]
	v_mfma_f32_16x16x32_bf16 v[126:129], v[114:117], v[150:153], v[126:129]
	v_mfma_f32_16x16x32_bf16 v[106:109], v[94:97], v[166:169], v[106:109]
	v_mfma_f32_16x16x32_bf16 v[102:105], v[114:117], v[166:169], v[102:105]
	v_mfma_f32_16x16x32_bf16 v[78:81], v[94:97], v[174:177], v[78:81]
	v_mfma_f32_16x16x32_bf16 v[74:77], v[114:117], v[174:177], v[74:77]
	v_mfma_f32_16x16x32_bf16 v[142:145], v[178:181], v[130:133], v[142:145]
	v_mfma_f32_16x16x32_bf16 v[122:125], v[186:189], v[130:133], v[122:125]
	v_mfma_f32_16x16x32_bf16 v[118:121], v[178:181], v[146:149], v[118:121]
	v_mfma_f32_16x16x32_bf16 v[110:113], v[186:189], v[146:149], v[110:113]
	v_mfma_f32_16x16x32_bf16 v[90:93], v[178:181], v[162:165], v[90:93]
	v_mfma_f32_16x16x32_bf16 v[86:89], v[186:189], v[162:165], v[86:89]
	v_mfma_f32_16x16x32_bf16 v[70:73], v[178:181], v[170:173], v[70:73]
	v_mfma_f32_16x16x32_bf16 v[66:69], v[186:189], v[170:173], v[66:69]
	v_mfma_f32_16x16x32_bf16 v[142:145], v[182:185], v[138:141], v[142:145]
	v_mfma_f32_16x16x32_bf16 v[138:141], v[190:193], v[138:141], v[122:125]
	v_mfma_f32_16x16x32_bf16 v[118:121], v[182:185], v[150:153], v[118:121]
	v_mfma_f32_16x16x32_bf16 v[110:113], v[190:193], v[150:153], v[110:113]
	v_mfma_f32_16x16x32_bf16 v[90:93], v[182:185], v[166:169], v[90:93]
	v_mfma_f32_16x16x32_bf16 v[86:89], v[190:193], v[166:169], v[86:89]
	v_mfma_f32_16x16x32_bf16 v[70:73], v[182:185], v[174:177], v[70:73]
	v_mfma_f32_16x16x32_bf16 v[66:69], v[190:193], v[174:177], v[66:69]
	s_setprio 0
	s_barrier
; #define PG8_STAGE(bufoff, gbase, voff) do { _Pragma("unroll") for (int _i = 0; _i < 2; ++_i) \
;         __builtin_amdgcn_global_load_lds((const unsigned*)((const char*)(gbase) + (voff)[_i]), (LAS unsigned*)(lds + (bufoff) + ldsw + _i * 8192), 16, 0, 0); } while (0)
; #define PG8_LDA(dst, b, h) do { _Pragma("unroll") for (int m = 0; m < 4; ++m) _Pragma("unroll") for (int k = 0; k < 2; ++k) dst[m][k] = *(const LAS bf16x8*)(lds + PG8_SA(b, h) + aoff + m * 2048 + k * 1024); } while (0)
; #define PG8_LDB(dst, b, h) do { _Pragma("unroll") for (int n = 0; n < 2; ++n) _Pragma("unroll") for (int k = 0; k < 2; ++k) dst[n][k] = *(const LAS bf16x8*)(lds + PG8_SB(b, h) + boff + n * 2048 + k * 1024); } while (0)
; #define PG8_WAIT_V(n) asm volatile("s_waitcnt vmcnt(" #n ")" ::: "memory")
; #define PG8_WAIT_L(n) asm volatile("s_waitcnt lgkmcnt(" #n ")" ::: "memory")
; #define PG8_BAR __builtin_amdgcn_s_barrier()
; #define PG8_SCHED __builtin_amdgcn_sched_barrier(0)
; template <class Epi>
; __device__ __forceinline__ void gemm_phase(LAS unsigned char* lds, const Gemm g, const Sched& S, const Epi& E) {
;     ...
;             PG8_LDB(B0, 1, 0); PG8_SCHED; PG8_LDA(At, 1, 0); PG8_STAGE(PG8_SA(0, 1), a2 + hstepA, voffA);
;             PG8_WAIT_L(8); PG8_BAR; PG8_WAIT_L(0); PG8_MMA(0, 0, At, B0); PG8_BAR; PG8_SCHED;
;             PG8_LDB(B1, 1, 1); PG8_STAGE(PG8_SB(1, 0), b3, voffB);
;             PG8_BAR; PG8_WAIT_L(0); PG8_MMA(0, 1, At, B1); PG8_BAR;
;             PG8_LDA(At, 1, 1); PG8_STAGE(PG8_SA(1, 0), a3, voffA);
;             PG8_BAR; PG8_WAIT_L(0); PG8_MMA(1, 0, At, B0); PG8_BAR; PG8_SCHED;
;             PG8_STAGE(PG8_SB(1, 1), b3 + hstepB, voffB);
;             PG8_WAIT_V(6); PG8_BAR; PG8_MMA(1, 1, At, B1); PG8_BAR;
;         }
;     __device__ __forceinline__ void operator()(const Acc& acc, const Unit& u, int wr, int wc, int fr, int fq, const Pre& pre) const {
;         const int row0 = u.pm * 256 + wr * 64 + fr, col0 = u.pn * 256 + wc * 32 + 8 * fq;
; #pragma unroll
;         for (int ai = 0; ai < 2; ++ai) {
;             u32x4 gw[4][2], pw[4][2];
; #pragma unroll
;             for (int m = 0; m < 4; ++m)
; #pragma unroll
;                 for (int bj = 0; bj < 2; ++bj) { const size_t off = (size_t)(row0 + ai * 128 + m * 16) * ldc + col0 + bj * 128;
;                     gw[m][bj] = *(const u32x4*)(gate + off); if (add) pw[m][bj] = *(const u32x4*)(O + off); }
	s_add_i32 s8, s8, s3
	v_lshl_add_u64 v[194:195], v[194:195], 0, s[60:61]
	s_mov_b32 m0, s8
	s_nop 0
	global_load_lds_dwordx4 v[194:195], off
	v_lshl_add_u64 v[194:195], v[206:207], 0, s[60:61]
	s_add_i32 m0, s8, 0x2000
	s_nop 0
	global_load_lds_dwordx4 v[194:195], off
	s_mov_b32 m0, s40
	v_lshl_add_u64 v[194:195], v[208:209], 0, s[60:61]
	ds_read_b128 v[122:125], v213 offset:49152
	ds_read_b128 v[130:133], v213 offset:50176
	ds_read_b128 v[146:149], v213 offset:51200
	ds_read_b128 v[150:153], v213 offset:52224
	ds_read_b128 v[162:165], v213 offset:53248
	ds_read_b128 v[166:169], v213 offset:54272
	ds_read_b128 v[170:173], v213 offset:55296
	ds_read_b128 v[174:177], v213 offset:56320
	global_load_lds_dwordx4 v[194:195], off
	v_lshl_add_u64 v[194:195], v[214:215], 0, s[60:61]
	s_mov_b32 m0, s41
	s_nop 0
	global_load_lds_dwordx4 v[194:195], off
	s_add_i32 s8, s9, s3
	v_lshl_add_u64 v[194:195], v[216:217], 0, s[60:61]
	s_mov_b32 m0, s8
	s_nop 0
	global_load_lds_dwordx4 v[194:195], off
	v_lshl_add_u64 v[194:195], v[222:223], 0, s[60:61]
	s_add_i32 m0, s8, 0x2000
	s_nop 0
	global_load_lds_dwordx4 v[194:195], off
	s_waitcnt vmcnt(8)
	s_waitcnt lgkmcnt(0)
	s_barrier
	s_setprio 1
	v_mfma_f32_16x16x32_bf16 v[62:65], v[82:85], v[122:125], v[62:65]
	v_mfma_f32_16x16x32_bf16 v[58:61], v[98:101], v[122:125], v[58:61]
	v_mfma_f32_16x16x32_bf16 v[46:49], v[82:85], v[146:149], v[46:49]
	v_mfma_f32_16x16x32_bf16 v[42:45], v[98:101], v[146:149], v[42:45]
	v_mfma_f32_16x16x32_bf16 v[30:33], v[82:85], v[162:165], v[30:33]
	v_mfma_f32_16x16x32_bf16 v[26:29], v[98:101], v[162:165], v[26:29]
	v_mfma_f32_16x16x32_bf16 v[14:17], v[82:85], v[170:173], v[14:17]
	v_mfma_f32_16x16x32_bf16 v[10:13], v[98:101], v[170:173], v[10:13]
	v_mfma_f32_16x16x32_bf16 v[62:65], v[94:97], v[130:133], v[62:65]
	v_mfma_f32_16x16x32_bf16 v[58:61], v[114:117], v[130:133], v[58:61]
	v_mfma_f32_16x16x32_bf16 v[46:49], v[94:97], v[150:153], v[46:49]
	v_mfma_f32_16x16x32_bf16 v[42:45], v[114:117], v[150:153], v[42:45]
	v_mfma_f32_16x16x32_bf16 v[30:33], v[94:97], v[166:169], v[30:33]
	v_mfma_f32_16x16x32_bf16 v[26:29], v[114:117], v[166:169], v[26:29]
	v_mfma_f32_16x16x32_bf16 v[14:17], v[94:97], v[174:177], v[14:17]
	v_mfma_f32_16x16x32_bf16 v[10:13], v[114:117], v[174:177], v[10:13]
	v_mfma_f32_16x16x32_bf16 v[54:57], v[178:181], v[122:125], v[54:57]
	v_mfma_f32_16x16x32_bf16 v[50:53], v[186:189], v[122:125], v[50:53]
	v_mfma_f32_16x16x32_bf16 v[38:41], v[178:181], v[146:149], v[38:41]
	v_mfma_f32_16x16x32_bf16 v[34:37], v[186:189], v[146:149], v[34:37]
	v_mfma_f32_16x16x32_bf16 v[22:25], v[178:181], v[162:165], v[22:25]
	v_mfma_f32_16x16x32_bf16 v[18:21], v[186:189], v[162:165], v[18:21]
	v_mfma_f32_16x16x32_bf16 v[6:9], v[178:181], v[170:173], v[6:9]
	v_mfma_f32_16x16x32_bf16 v[2:5], v[186:189], v[170:173], v[2:5]
	v_mfma_f32_16x16x32_bf16 v[54:57], v[182:185], v[130:133], v[54:57]
	v_mfma_f32_16x16x32_bf16 v[50:53], v[190:193], v[130:133], v[50:53]
	v_mfma_f32_16x16x32_bf16 v[38:41], v[182:185], v[150:153], v[38:41]
	v_mfma_f32_16x16x32_bf16 v[34:37], v[190:193], v[150:153], v[34:37]
	v_mfma_f32_16x16x32_bf16 v[22:25], v[182:185], v[166:169], v[22:25]
	v_mfma_f32_16x16x32_bf16 v[18:21], v[190:193], v[166:169], v[18:21]
	v_mfma_f32_16x16x32_bf16 v[6:9], v[182:185], v[174:177], v[6:9]
	v_mfma_f32_16x16x32_bf16 v[2:5], v[190:193], v[174:177], v[2:5]
	s_setprio 0
	s_add_u32 s4, s4, 0x100
	s_addc_u32 s5, s5, 0
	s_add_u32 s34, s34, 0x100
	s_addc_u32 s35, s35, 0
	s_cmp_ge_u32 s14, s73
	s_mov_b32 s88, s14
	s_barrier
	s_cbranch_scc0 .LBB0_461
	v_lshl_add_u32 v214, s67, 8, v210
	v_lshl_or_b32 v206, s55, 8, v212
	v_ashrrev_i32_e32 v207, 31, v206
	v_ashrrev_i32_e32 v82, 31, v214
	v_mul_lo_u32 v215, s12, v82
	v_mul_lo_u32 v238, s13, v214
	v_mad_u64_u32 v[82:83], s[4:5], s12, v214, v[206:207]
	v_add3_u32 v83, v238, v83, v215
	v_lshl_add_u64 v[84:85], v[82:83], 1, s[6:7]
	global_load_dwordx4 v[190:193], v[84:85], off
	v_cndmask_b32_e64 v94, 0, 1, s[76:77]
	v_cmp_ne_u32_e64 s[4:5], 1, v94
	s_andn2_b64 vcc, exec, s[76:77]
	v_lshl_add_u64 v[82:83], v[82:83], 1, s[62:63]
	s_cbranch_vccnz .LBB0_464
	global_load_dwordx4 v[150:153], v[82:83], off

; __device__ __forceinline__ int otid() { int t = threadIdx.x; asm volatile("" : "+v"(t)); return t; }
; #define PG8_STAGE(bufoff, gbase, voff) do { _Pragma("unroll") for (int _i = 0; _i < 2; ++_i) \
;         __builtin_amdgcn_global_load_lds((const unsigned*)((const char*)(gbase) + (voff)[_i]), (LAS unsigned*)(lds + (bufoff) + ldsw + _i * 8192), 16, 0, 0); } while (0)
; #define PG8_WAIT_V(n) asm volatile("s_waitcnt vmcnt(" #n ")" ::: "memory")
; #define PG8_BAR __builtin_amdgcn_s_barrier()
;     __device__ __forceinline__ Pre prefetch(const Unit& u, int wr, int fr) const { return pre_rows(ss, u.pm * 256 + wr * 64 + (int)(threadIdx.x & 63)); }
;     __device__ __forceinline__ Pre prefetch(const Unit& u, int wr, int fr) const { return pre_rows(ss, u.pm * 256 + wr * 64 + (int)(threadIdx.x & 63)); }
; template <class Epi>
; __device__ __forceinline__ void gemm_phase(LAS unsigned char* lds, const Gemm g, const Sched& S, const Epi& E) {
;     const int tid = otid(), wid = __builtin_amdgcn_readfirstlane(tid >> 6), lane = tid & 63, wr = wid >> 2, wc = wid & 3, fr = lane & 15, fq = lane >> 4;
;     const int nt = g.K / BK;
;     unsigned voffA[2], voffB[2];
; #pragma unroll
;     for (int i = 0; i < 2; ++i) { int R, C; stage_rc(tid * 16 + i * 8192, R, C); const int Rb = Epi::PERM ? ((R & ~31) + perm32(R & 31)) : R;
;         voffA[i] = (unsigned)(R * g.lda + C) * 2u; voffB[i] = (unsigned)(Rb * g.ldb + C) * 2u; }
;     const size_t kstep = (size_t)(BK * 2);
;     const size_t hstepA = (size_t)HALF * g.lda * 2, hstepB = (size_t)HALF * g.ldb * 2;
;     const unsigned ldsw = (unsigned)wid * 1024u;
;     const int aoff = lds_byte(wr * 64 + fr, fq * 8), boff = lds_byte(wc * 32 + fr, fq * 8);
;     ...
;     PG8_STAGE(PG8_SB(0, 0), cB, voffB); PG8_STAGE(PG8_SA(0, 0), cA, voffA); PG8_STAGE(PG8_SB(0, 1), cB + hstepB, voffB); PG8_STAGE(PG8_SA(0, 1), cA + hstepA, voffA);
;     if (wr == 1) PG8_BAR;
;     PG8_WAIT_V(4); PG8_BAR;
;     PG8_STAGE(PG8_SB(1, 0), cB + kstep, voffB); PG8_STAGE(PG8_SA(1, 0), cA + kstep, voffA); PG8_STAGE(PG8_SB(1, 1), cB + hstepB + kstep, voffB);
;     PG8_WAIT_V(6); PG8_BAR;
;     for (;;) {
;         const Pre pre = E.prefetch(cur, wr, fr);
;         const bool has_next = S.next(ui + 1, nxt);
;         const char* nA = has_next ? (const char*)g.A + nxt.ao : cA; const char* nB = has_next ? (const char*)g.Bt + nxt.bo : cB;
.LBB0_541:
	s_add_i32 m0, s33, 0x18000
	v_lshl_add_u64 v[2:3], v[2:3], 0, s[60:61]
	s_waitcnt vmcnt(0)
	s_barrier
	global_load_lds_dwordx4 v[2:3], off
	v_lshl_add_u64 v[2:3], v[4:5], 0, s[60:61]
	s_add_i32 m0, s33, 0x1a000
	s_add_i32 s41, s33, 0x8000
	global_load_lds_dwordx4 v[2:3], off
	v_lshl_add_u64 v[2:3], v[6:7], 0, s[60:61]
	s_mov_b32 m0, s41
	s_add_i32 s42, s33, 0xa000
	global_load_lds_dwordx4 v[2:3], off
	v_lshl_add_u64 v[2:3], v[8:9], 0, s[60:61]
	s_mov_b32 m0, s42
	v_lshrrev_b32_e32 v21, 1, v16
	global_load_lds_dwordx4 v[2:3], off
	s_add_i32 m0, s33, 0x1c000
	v_lshl_add_u64 v[2:3], v[10:11], 0, s[60:61]
	global_load_lds_dwordx4 v[2:3], off
	v_lshl_add_u64 v[2:3], v[12:13], 0, s[60:61]
	s_add_i32 m0, s33, 0x1e000
	v_and_b32_e32 v21, 24, v21
	global_load_lds_dwordx4 v[2:3], off
	v_and_b32_e32 v154, 15, v16
	s_lshl_b32 s8, s1, 6
	v_lshlrev_b32_e32 v22, 1, v21
	v_lshlrev_b32_e32 v16, 2, v16
	s_lshl_b32 s0, s0, 5
	v_and_b32_e32 v2, 63, v219
	v_or_b32_e32 v155, s8, v154
	v_lshl_or_b32 v22, v154, 6, v22
	s_lshl_b32 s1, s1, 13
	v_and_b32_e32 v16, 32, v16
	s_and_b32 s0, s0, 0x60
	v_or_b32_e32 v157, s8, v2
	v_readlane_b32 s8, v253, 61
	v_bitop3_b32 v23, v22, s1, v16 bitop3:0xde
	s_lshl_b32 s1, s0, 7
	s_add_i32 s43, s73, -2
	v_readlane_b32 s9, v253, 62
	s_cmp_eq_u64 s[8:9], 0
	v_bitop3_b32 v156, v22, s1, v16 bitop3:0xde
	s_cselect_b64 s[78:79], -1, 0
	s_cmp_lg_u64 s[8:9], 0
	v_readlane_b32 s1, v254, 13
	s_cselect_b64 s[80:81], -1, 0
	s_ashr_i32 s48, s1, 31
	s_lshr_b32 s1, s54, 3
	v_writelane_b32 v254, s1, 33
	s_add_i32 s1, s1, 1
	v_readlane_b32 s8, v253, 30
	v_writelane_b32 v254, s1, 31
	v_or_b32_e32 v158, s0, v21
	v_readlane_b32 s1, v254, 5
	v_readlane_b32 s8, v254, 37
	s_mul_i32 s24, s1, s8
	v_cvt_f32_u32_e32 v2, s24
	s_sub_i32 s0, 0, s24
	v_mov_b32_e32 v3, v1
	s_waitcnt vmcnt(6)
	v_rcp_iflag_f32_e32 v2, v2
	v_readlane_b32 s9, v253, 31
	s_mov_b32 s27, s9
	s_and_b32 s52, s54, 7
	v_mul_f32_e32 v2, 0x4f7ffffe, v2
	v_cvt_u32_f32_e32 v2, v2
	s_mov_b32 s56, 0
	v_add_u32_e32 v159, 0, v23
	s_barrier
	v_readfirstlane_b32 s1, v2
	v_cvt_f32_u32_e32 v2, s25
	s_mul_i32 s0, s0, s1
	s_mul_hi_u32 s0, s1, s0
	s_add_i32 s58, s1, s0
	v_rcp_iflag_f32_e32 v2, v2
	s_sub_i32 s0, 0, s25
	v_mul_f32_e32 v2, 0x4f7ffffe, v2
	v_cvt_u32_f32_e32 v2, v2
	s_nop 0
	v_readfirstlane_b32 s1, v2
	v_add_u32_e32 v2, v17, v14
	v_add_lshl_u32 v2, v2, v15, 1
	s_mul_i32 s0, s0, s1
	v_lshl_add_u64 v[136:137], s[36:37], 0, v[2:3]
	v_add_u32_e32 v2, v20, v18
	s_mul_hi_u32 s0, s1, s0
	v_add_lshl_u32 v2, v2, v19, 1
	s_add_i32 s64, s1, s0
	v_lshl_add_u64 v[138:139], s[36:37], 0, v[2:3]
	s_branch .LBB0_543

; #define PG8_STAGE(bufoff, gbase, voff) do { _Pragma("unroll") for (int _i = 0; _i < 2; ++_i) \
;         __builtin_amdgcn_global_load_lds((const unsigned*)((const char*)(gbase) + (voff)[_i]), (LAS unsigned*)(lds + (bufoff) + ldsw + _i * 8192), 16, 0, 0); } while (0)
; #define PG8_LDA(dst, b, h) do { _Pragma("unroll") for (int m = 0; m < 4; ++m) _Pragma("unroll") for (int k = 0; k < 2; ++k) dst[m][k] = *(const LAS bf16x8*)(lds + PG8_SA(b, h) + aoff + m * 2048 + k * 1024); } while (0)
; #define PG8_LDB(dst, b, h) do { _Pragma("unroll") for (int n = 0; n < 2; ++n) _Pragma("unroll") for (int k = 0; k < 2; ++k) dst[n][k] = *(const LAS bf16x8*)(lds + PG8_SB(b, h) + boff + n * 2048 + k * 1024); } while (0)
; #define PG8_MMA(ai, bj, At, Bt) do { __builtin_amdgcn_s_setprio(1); _Pragma("unroll") for (int m = 0; m < 4; ++m) _Pragma("unroll") for (int n = 0; n < 2; ++n) _Pragma("unroll") for (int k = 0; k < 2; ++k) \
;         acc[ai][bj][m][n] = __builtin_amdgcn_mfma_f32_16x16x32_bf16(Bt[n][k], At[m][k], acc[ai][bj][m][n], 0, 0, 0); __builtin_amdgcn_s_setprio(0); } while (0)
; #define PG8_WAIT_L(n) asm volatile("s_waitcnt lgkmcnt(" #n ")" ::: "memory")
; #define PG8_BAR __builtin_amdgcn_s_barrier()
; #define PG8_SCHED __builtin_amdgcn_sched_barrier(0)
; template <class Epi>
; __device__ __forceinline__ void gemm_phase(LAS unsigned char* lds, const Gemm g, const Sched& S, const Epi& E) {
;     ...
;         for (int t = 0; t < nt; t += 2) {
;             const bool last = (t == nt - 2);
;             const char* a1 = cA + (size_t)(t + 1) * kstep;
;             const char* a2 = last ? nA : cA + (size_t)(t + 2) * kstep; const char* b2 = last ? nB : cB + (size_t)(t + 2) * kstep;
;             const char* a3 = a2 + kstep; const char* b3 = b2 + kstep;
;             PG8_LDB(B0, 0, 0); PG8_SCHED; PG8_LDA(At, 0, 0); PG8_STAGE(PG8_SA(1, 1), a1 + hstepA, voffA);
;             PG8_WAIT_L(8); PG8_BAR; PG8_WAIT_L(0); PG8_MMA(0, 0, At, B0); PG8_BAR; PG8_SCHED;
;             PG8_LDB(B1, 0, 1); PG8_STAGE(PG8_SB(0, 0), b2, voffB);
;             PG8_BAR; PG8_WAIT_L(0); PG8_MMA(0, 1, At, B1); PG8_BAR;
;             PG8_LDA(At, 0, 1); PG8_STAGE(PG8_SA(0, 0), a2, voffA);
.LBB0_555:
	s_add_i32 s14, s6, 2
	s_add_u32 s8, s4, 0x80
	s_addc_u32 s7, s5, 0
	s_add_i32 s9, 0, 0x10000
	v_add_u32_e32 v160, s9, v156
	ds_read_b128 v[142:145], v160
	ds_read_b128 v[146:149], v160 offset:1024
	ds_read_b128 v[150:153], v160 offset:2048
	ds_read_b128 v[160:163], v160 offset:3072
	s_cmp_eq_u32 s43, s6
	s_cselect_b32 s6, s57, s8
	s_cselect_b32 s7, s55, s7
	s_cselect_b32 s91, s59, s35
	s_cselect_b32 s90, s95, s34
	v_lshl_add_u64 v[192:193], s[4:5], 0, v[136:137]
	s_add_i32 m0, s33, 0xc000
	ds_read_b128 v[164:167], v159
	ds_read_b128 v[168:171], v159 offset:1024
	ds_read_b128 v[172:175], v159 offset:2048
	ds_read_b128 v[176:179], v159 offset:3072
	ds_read_b128 v[180:183], v159 offset:4096
	ds_read_b128 v[184:187], v159 offset:5120
	ds_read_b128 v[188:191], v159 offset:6144
	ds_read_b128 v[196:199], v159 offset:7168
	global_load_lds_dwordx4 v[192:193], off
	v_lshl_add_u64 v[192:193], s[4:5], 0, v[138:139]
	s_add_i32 m0, s33, 0xe000
	s_nop 0
	global_load_lds_dwordx4 v[192:193], off
	s_add_i32 s8, 0, 0x14000
	v_add_u32_e32 v192, s8, v156
	ds_read_b128 v[200:203], v192
	ds_read_b128 v[204:207], v192 offset:1024
	ds_read_b128 v[208:211], v192 offset:2048
	ds_read_b128 v[212:215], v192 offset:3072
	s_waitcnt vmcnt(8)
	s_waitcnt lgkmcnt(0)
	s_barrier
	s_setprio 1
	v_mfma_f32_16x16x32_bf16 v[126:129], v[142:145], v[164:167], v[126:129]
	v_mfma_f32_16x16x32_bf16 v[122:125], v[150:153], v[164:167], v[122:125]
	v_mfma_f32_16x16x32_bf16 v[110:113], v[142:145], v[172:175], v[110:113]
	v_mfma_f32_16x16x32_bf16 v[106:109], v[150:153], v[172:175], v[106:109]
	v_mfma_f32_16x16x32_bf16 v[94:97], v[142:145], v[180:183], v[94:97]
	v_mfma_f32_16x16x32_bf16 v[90:93], v[150:153], v[180:183], v[90:93]
	v_mfma_f32_16x16x32_bf16 v[78:81], v[142:145], v[188:191], v[78:81]
	v_mfma_f32_16x16x32_bf16 v[74:77], v[150:153], v[188:191], v[74:77]
	v_mfma_f32_16x16x32_bf16 v[126:129], v[146:149], v[168:171], v[126:129]
	v_mfma_f32_16x16x32_bf16 v[122:125], v[160:163], v[168:171], v[122:125]
	v_mfma_f32_16x16x32_bf16 v[110:113], v[146:149], v[176:179], v[110:113]
	v_mfma_f32_16x16x32_bf16 v[106:109], v[160:163], v[176:179], v[106:109]
	v_mfma_f32_16x16x32_bf16 v[94:97], v[146:149], v[184:187], v[94:97]
	v_mfma_f32_16x16x32_bf16 v[90:93], v[160:163], v[184:187], v[90:93]
	v_mfma_f32_16x16x32_bf16 v[78:81], v[146:149], v[196:199], v[78:81]
	v_mfma_f32_16x16x32_bf16 v[74:77], v[160:163], v[196:199], v[74:77]
	v_mfma_f32_16x16x32_bf16 v[118:121], v[200:203], v[164:167], v[118:121]
	v_mfma_f32_16x16x32_bf16 v[114:117], v[208:211], v[164:167], v[114:117]
	v_mfma_f32_16x16x32_bf16 v[102:105], v[200:203], v[172:175], v[102:105]
	v_mfma_f32_16x16x32_bf16 v[98:101], v[208:211], v[172:175], v[98:101]
	v_mfma_f32_16x16x32_bf16 v[86:89], v[200:203], v[180:183], v[86:89]
	v_mfma_f32_16x16x32_bf16 v[82:85], v[208:211], v[180:183], v[82:85]
	v_mfma_f32_16x16x32_bf16 v[70:73], v[200:203], v[188:191], v[70:73]
	v_mfma_f32_16x16x32_bf16 v[66:69], v[208:211], v[188:191], v[66:69]
	v_mfma_f32_16x16x32_bf16 v[118:121], v[204:207], v[168:171], v[118:121]
	v_mfma_f32_16x16x32_bf16 v[114:117], v[212:215], v[168:171], v[114:117]
	v_mfma_f32_16x16x32_bf16 v[102:105], v[204:207], v[176:179], v[102:105]
	v_mfma_f32_16x16x32_bf16 v[98:101], v[212:215], v[176:179], v[98:101]
	v_mfma_f32_16x16x32_bf16 v[86:89], v[204:207], v[184:187], v[86:89]
	v_mfma_f32_16x16x32_bf16 v[82:85], v[212:215], v[184:187], v[82:85]
	v_mfma_f32_16x16x32_bf16 v[70:73], v[204:207], v[196:199], v[70:73]
	v_mfma_f32_16x16x32_bf16 v[66:69], v[212:215], v[196:199], v[66:69]
	s_setprio 0
	s_barrier
	s_add_i32 s9, s9, s3
	v_lshl_add_u64 v[192:193], s[90:91], 0, v[0:1]
	s_mov_b32 m0, s9
	v_lshl_add_u64 v[194:195], s[90:91], 0, v[134:135]
	global_load_lds_dwordx4 v[192:193], off
	s_add_i32 m0, s9, 0x2000
	s_nop 0
	global_load_lds_dwordx4 v[194:195], off
	s_mov_b32 m0, s33
	v_lshl_add_u64 v[216:217], s[6:7], 0, v[130:131]
	ds_read_b128 v[164:167], v159 offset:16384
	ds_read_b128 v[168:171], v159 offset:17408
	ds_read_b128 v[172:175], v159 offset:18432
	ds_read_b128 v[176:179], v159 offset:19456
	ds_read_b128 v[180:183], v159 offset:20480
	ds_read_b128 v[184:187], v159 offset:21504
	ds_read_b128 v[188:191], v159 offset:22528
	ds_read_b128 v[196:199], v159 offset:23552
	global_load_lds_dwordx4 v[216:217], off
	v_lshl_add_u64 v[222:223], s[6:7], 0, v[132:133]
	s_mov_b32 m0, s38
	s_nop 0
	global_load_lds_dwordx4 v[222:223], off
	s_add_u32 s90, s90, s76
	s_addc_u32 s91, s91, s77
	s_add_i32 s8, s8, s3
	v_lshl_add_u64 v[224:225], s[90:91], 0, v[0:1]
	s_mov_b32 m0, s8
	v_lshl_add_u64 v[226:227], s[90:91], 0, v[134:135]
	global_load_lds_dwordx4 v[224:225], off
	s_add_i32 m0, s8, 0x2000
	s_nop 0
	global_load_lds_dwordx4 v[226:227], off
	s_waitcnt vmcnt(8)
	s_waitcnt lgkmcnt(0)
	s_barrier
; #define PG8_STAGE(bufoff, gbase, voff) do { _Pragma("unroll") for (int _i = 0; _i < 2; ++_i) \
;         __builtin_amdgcn_global_load_lds((const unsigned*)((const char*)(gbase) + (voff)[_i]), (LAS unsigned*)(lds + (bufoff) + ldsw + _i * 8192), 16, 0, 0); } while (0)
; #define PG8_LDA(dst, b, h) do { _Pragma("unroll") for (int m = 0; m < 4; ++m) _Pragma("unroll") for (int k = 0; k < 2; ++k) dst[m][k] = *(const LAS bf16x8*)(lds + PG8_SA(b, h) + aoff + m * 2048 + k * 1024); } while (0)
; #define PG8_LDB(dst, b, h) do { _Pragma("unroll") for (int n = 0; n < 2; ++n) _Pragma("unroll") for (int k = 0; k < 2; ++k) dst[n][k] = *(const LAS bf16x8*)(lds + PG8_SB(b, h) + boff + n * 2048 + k * 1024); } while (0)
; #define PG8_MMA(ai, bj, At, Bt) do { __builtin_amdgcn_s_setprio(1); _Pragma("unroll") for (int m = 0; m < 4; ++m) _Pragma("unroll") for (int n = 0; n < 2; ++n) _Pragma("unroll") for (int k = 0; k < 2; ++k) \
;         acc[ai][bj][m][n] = __builtin_amdgcn_mfma_f32_16x16x32_bf16(Bt[n][k], At[m][k], acc[ai][bj][m][n], 0, 0, 0); __builtin_amdgcn_s_setprio(0); } while (0)
; #define PG8_WAIT_V(n) asm volatile("s_waitcnt vmcnt(" #n ")" ::: "memory")
; #define PG8_WAIT_L(n) asm volatile("s_waitcnt lgkmcnt(" #n ")" ::: "memory")
; #define PG8_BAR __builtin_amdgcn_s_barrier()
; #define PG8_SCHED __builtin_amdgcn_sched_barrier(0)
; template <class Epi>
; __device__ __forceinline__ void gemm_phase(LAS unsigned char* lds, const Gemm g, const Sched& S, const Epi& E) {
;     ...
;             PG8_BAR; PG8_WAIT_L(0); PG8_MMA(0, 1, At, B1); PG8_BAR;
;             PG8_LDA(At, 0, 1); PG8_STAGE(PG8_SA(0, 0), a2, voffA);
;             PG8_BAR; PG8_WAIT_L(0); PG8_MMA(1, 0, At, B0); PG8_BAR; PG8_SCHED;
;             PG8_STAGE(PG8_SB(0, 1), b2 + hstepB, voffB);
;             PG8_WAIT_V(6); PG8_BAR; PG8_MMA(1, 1, At, B1); PG8_BAR;
;             PG8_LDB(B0, 1, 0); PG8_SCHED; PG8_LDA(At, 1, 0); PG8_STAGE(PG8_SA(0, 1), a2 + hstepA, voffA);
;             PG8_WAIT_L(8); PG8_BAR; PG8_WAIT_L(0); PG8_MMA(0, 0, At, B0); PG8_BAR; PG8_SCHED;
	s_setprio 1
	v_mfma_f32_16x16x32_bf16 v[62:65], v[142:145], v[164:167], v[62:65]
	v_mfma_f32_16x16x32_bf16 v[58:61], v[150:153], v[164:167], v[58:61]
	v_mfma_f32_16x16x32_bf16 v[46:49], v[142:145], v[172:175], v[46:49]
	v_mfma_f32_16x16x32_bf16 v[42:45], v[150:153], v[172:175], v[42:45]
	v_mfma_f32_16x16x32_bf16 v[30:33], v[142:145], v[180:183], v[30:33]
	v_mfma_f32_16x16x32_bf16 v[26:29], v[150:153], v[180:183], v[26:29]
	v_mfma_f32_16x16x32_bf16 v[14:17], v[142:145], v[188:191], v[14:17]
	v_mfma_f32_16x16x32_bf16 v[10:13], v[150:153], v[188:191], v[10:13]
	v_mfma_f32_16x16x32_bf16 v[62:65], v[146:149], v[168:171], v[62:65]
	v_mfma_f32_16x16x32_bf16 v[58:61], v[160:163], v[168:171], v[58:61]
	v_mfma_f32_16x16x32_bf16 v[46:49], v[146:149], v[176:179], v[46:49]
	v_mfma_f32_16x16x32_bf16 v[42:45], v[160:163], v[176:179], v[42:45]
	v_mfma_f32_16x16x32_bf16 v[30:33], v[146:149], v[184:187], v[30:33]
	v_mfma_f32_16x16x32_bf16 v[26:29], v[160:163], v[184:187], v[26:29]
	v_mfma_f32_16x16x32_bf16 v[14:17], v[146:149], v[196:199], v[14:17]
	v_mfma_f32_16x16x32_bf16 v[10:13], v[160:163], v[196:199], v[10:13]
	v_mfma_f32_16x16x32_bf16 v[54:57], v[200:203], v[164:167], v[54:57]
	v_mfma_f32_16x16x32_bf16 v[50:53], v[208:211], v[164:167], v[50:53]
	v_mfma_f32_16x16x32_bf16 v[38:41], v[200:203], v[172:175], v[38:41]
	v_mfma_f32_16x16x32_bf16 v[34:37], v[208:211], v[172:175], v[34:37]
	v_mfma_f32_16x16x32_bf16 v[22:25], v[200:203], v[180:183], v[22:25]
	v_mfma_f32_16x16x32_bf16 v[18:21], v[208:211], v[180:183], v[18:21]
	v_mfma_f32_16x16x32_bf16 v[6:9], v[200:203], v[188:191], v[6:9]
	v_mfma_f32_16x16x32_bf16 v[2:5], v[208:211], v[188:191], v[2:5]
	v_mfma_f32_16x16x32_bf16 v[54:57], v[204:207], v[168:171], v[54:57]
	v_mfma_f32_16x16x32_bf16 v[50:53], v[212:215], v[168:171], v[50:53]
	v_mfma_f32_16x16x32_bf16 v[38:41], v[204:207], v[176:179], v[38:41]
	v_mfma_f32_16x16x32_bf16 v[34:37], v[212:215], v[176:179], v[34:37]
	v_mfma_f32_16x16x32_bf16 v[22:25], v[204:207], v[184:187], v[22:25]
	v_mfma_f32_16x16x32_bf16 v[18:21], v[212:215], v[184:187], v[18:21]
	v_mfma_f32_16x16x32_bf16 v[6:9], v[204:207], v[196:199], v[6:9]
	v_mfma_f32_16x16x32_bf16 v[2:5], v[212:215], v[196:199], v[2:5]
	s_setprio 0
	s_barrier
	s_add_i32 s8, 0, 0x18000
	v_add_u32_e32 v160, s8, v156
	ds_read_b128 v[142:145], v160
	ds_read_b128 v[146:149], v160 offset:1024
	ds_read_b128 v[150:153], v160 offset:2048
	ds_read_b128 v[160:163], v160 offset:3072
	s_add_u32 s6, s6, s36
	s_addc_u32 s7, s7, s37
	s_mov_b32 m0, s39
	v_lshl_add_u64 v[200:201], s[6:7], 0, v[130:131]
	ds_read_b128 v[164:167], v159 offset:32768
	ds_read_b128 v[168:171], v159 offset:33792
	ds_read_b128 v[172:175], v159 offset:34816
	ds_read_b128 v[176:179], v159 offset:35840
	ds_read_b128 v[180:183], v159 offset:36864
	ds_read_b128 v[184:187], v159 offset:37888
	ds_read_b128 v[188:191], v159 offset:38912
	ds_read_b128 v[196:199], v159 offset:39936
	global_load_lds_dwordx4 v[200:201], off
	v_lshl_add_u64 v[200:201], s[6:7], 0, v[132:133]
	s_mov_b32 m0, s40
	s_nop 0
	global_load_lds_dwordx4 v[200:201], off
	s_add_i32 s6, 0, 0x1c000
	v_add_u32_e32 v212, s6, v156
	ds_read_b128 v[200:203], v212
	ds_read_b128 v[204:207], v212 offset:1024
	ds_read_b128 v[208:211], v212 offset:2048
	ds_read_b128 v[212:215], v212 offset:3072
	s_waitcnt vmcnt(8)
	s_waitcnt lgkmcnt(0)
	s_barrier
	s_setprio 1
	v_mfma_f32_16x16x32_bf16 v[126:129], v[142:145], v[164:167], v[126:129]
	v_mfma_f32_16x16x32_bf16 v[122:125], v[150:153], v[164:167], v[122:125]
	v_mfma_f32_16x16x32_bf16 v[110:113], v[142:145], v[172:175], v[110:113]
	v_mfma_f32_16x16x32_bf16 v[106:109], v[150:153], v[172:175], v[106:109]
	v_mfma_f32_16x16x32_bf16 v[94:97], v[142:145], v[180:183], v[94:97]
	v_mfma_f32_16x16x32_bf16 v[90:93], v[150:153], v[180:183], v[90:93]
	v_mfma_f32_16x16x32_bf16 v[78:81], v[142:145], v[188:191], v[78:81]
	v_mfma_f32_16x16x32_bf16 v[74:77], v[150:153], v[188:191], v[74:77]
	v_mfma_f32_16x16x32_bf16 v[126:129], v[146:149], v[168:171], v[126:129]
	v_mfma_f32_16x16x32_bf16 v[122:125], v[160:163], v[168:171], v[122:125]
	v_mfma_f32_16x16x32_bf16 v[110:113], v[146:149], v[176:179], v[110:113]
	v_mfma_f32_16x16x32_bf16 v[106:109], v[160:163], v[176:179], v[106:109]
	v_mfma_f32_16x16x32_bf16 v[94:97], v[146:149], v[184:187], v[94:97]
	v_mfma_f32_16x16x32_bf16 v[90:93], v[160:163], v[184:187], v[90:93]
	v_mfma_f32_16x16x32_bf16 v[78:81], v[146:149], v[196:199], v[78:81]
	v_mfma_f32_16x16x32_bf16 v[74:77], v[160:163], v[196:199], v[74:77]
	v_mfma_f32_16x16x32_bf16 v[118:121], v[200:203], v[164:167], v[118:121]
	v_mfma_f32_16x16x32_bf16 v[114:117], v[208:211], v[164:167], v[114:117]
	v_mfma_f32_16x16x32_bf16 v[102:105], v[200:203], v[172:175], v[102:105]
	v_mfma_f32_16x16x32_bf16 v[98:101], v[208:211], v[172:175], v[98:101]
	v_mfma_f32_16x16x32_bf16 v[86:89], v[200:203], v[180:183], v[86:89]
	v_mfma_f32_16x16x32_bf16 v[82:85], v[208:211], v[180:183], v[82:85]
	v_mfma_f32_16x16x32_bf16 v[70:73], v[200:203], v[188:191], v[70:73]
	v_mfma_f32_16x16x32_bf16 v[66:69], v[208:211], v[188:191], v[66:69]
	v_mfma_f32_16x16x32_bf16 v[118:121], v[204:207], v[168:171], v[118:121]
	v_mfma_f32_16x16x32_bf16 v[114:117], v[212:215], v[168:171], v[114:117]
	v_mfma_f32_16x16x32_bf16 v[102:105], v[204:207], v[176:179], v[102:105]
	v_mfma_f32_16x16x32_bf16 v[98:101], v[212:215], v[176:179], v[98:101]
	v_mfma_f32_16x16x32_bf16 v[86:89], v[204:207], v[184:187], v[86:89]
	v_mfma_f32_16x16x32_bf16 v[82:85], v[212:215], v[184:187], v[82:85]
	v_mfma_f32_16x16x32_bf16 v[70:73], v[204:207], v[196:199], v[70:73]
	v_mfma_f32_16x16x32_bf16 v[66:69], v[212:215], v[196:199], v[66:69]
	s_setprio 0
	s_barrier
; __device__ __forceinline__ float pre_get(const Pre& p, int ai, int m, int fr) { return __shfl(p.v[ai], m * 16 + fr); }
; __device__ __forceinline__ float rstd_pre(const float* ss, float v) { return ss ? rsqrtf(v * (1.0f / 2048.0f) + 1e-6f) : 1.0f; }
; #define PG8_STAGE(bufoff, gbase, voff) do { _Pragma("unroll") for (int _i = 0; _i < 2; ++_i) \
;         __builtin_amdgcn_global_load_lds((const unsigned*)((const char*)(gbase) + (voff)[_i]), (LAS unsigned*)(lds + (bufoff) + ldsw + _i * 8192), 16, 0, 0); } while (0)
; #define PG8_LDA(dst, b, h) do { _Pragma("unroll") for (int m = 0; m < 4; ++m) _Pragma("unroll") for (int k = 0; k < 2; ++k) dst[m][k] = *(const LAS bf16x8*)(lds + PG8_SA(b, h) + aoff + m * 2048 + k * 1024); } while (0)
; template <class Epi>
; __device__ __forceinline__ void gemm_phase(LAS unsigned char* lds, const Gemm g, const Sched& S, const Epi& E) {
;     ...
;             PG8_LDB(B0, 1, 0); PG8_SCHED; PG8_LDA(At, 1, 0); PG8_STAGE(PG8_SA(0, 1), a2 + hstepA, voffA);
;             PG8_WAIT_L(8); PG8_BAR; PG8_WAIT_L(0); PG8_MMA(0, 0, At, B0); PG8_BAR; PG8_SCHED;
;             PG8_LDB(B1, 1, 1); PG8_STAGE(PG8_SB(1, 0), b3, voffB);
;             PG8_BAR; PG8_WAIT_L(0); PG8_MMA(0, 1, At, B1); PG8_BAR;
;             PG8_LDA(At, 1, 1); PG8_STAGE(PG8_SA(1, 0), a3, voffA);
;             PG8_BAR; PG8_WAIT_L(0); PG8_MMA(1, 0, At, B0); PG8_BAR; PG8_SCHED;
;             PG8_STAGE(PG8_SB(1, 1), b3 + hstepB, voffB);
;             PG8_WAIT_V(6); PG8_BAR; PG8_MMA(1, 1, At, B1); PG8_BAR;
;         }
;     __device__ __forceinline__ void operator()(const Acc& acc, const Unit& u, int wr, int wc, int fr, int fq, const Pre& pre) const {
;         const int colt = (u.pn < split) ? base0 + u.pn * 256 : base1 + (u.pn - split) * 256;
;         const int row0 = u.pm * 256 + wr * 64 + fr, col0 = colt + wc * 32 + 8 * fq;
;         bf16_t* Oz = O + (size_t)(u.zb * sOb + u.zh * sOh);
;         float rsq[2][4];
; #pragma unroll
;         for (int ai = 0; ai < 2; ++ai)
; #pragma unroll
;             for (int m = 0; m < 4; ++m) rsq[ai][m] = rstd_pre(ss, pre_get(pre, ai, m, fr));
; #pragma unroll
;         for (int ai = 0; ai < 2; ++ai)
; #pragma unroll
;             for (int m = 0; m < 4; ++m) { const float rs = scale * rsq[ai][m];
; #pragma unroll
;                 for (int bj = 0; bj < 2; ++bj) { f32x4 v0 = acc[ai][bj][m][0] * rs, v1 = acc[ai][bj][m][1] * rs;
	s_add_i32 s7, s8, s3
	v_lshl_add_u64 v[192:193], v[192:193], 0, s[60:61]
	s_mov_b32 m0, s7
	s_nop 0
	global_load_lds_dwordx4 v[192:193], off
	v_lshl_add_u64 v[192:193], v[194:195], 0, s[60:61]
	s_add_i32 m0, s7, 0x2000
	s_nop 0
	global_load_lds_dwordx4 v[192:193], off
	s_mov_b32 m0, s41
	v_lshl_add_u64 v[192:193], v[216:217], 0, s[60:61]
	ds_read_b128 v[164:167], v159 offset:49152
	ds_read_b128 v[168:171], v159 offset:50176
	ds_read_b128 v[172:175], v159 offset:51200
	ds_read_b128 v[176:179], v159 offset:52224
	ds_read_b128 v[180:183], v159 offset:53248
	ds_read_b128 v[184:187], v159 offset:54272
	ds_read_b128 v[188:191], v159 offset:55296
	ds_read_b128 v[196:199], v159 offset:56320
	global_load_lds_dwordx4 v[192:193], off
	v_lshl_add_u64 v[192:193], v[222:223], 0, s[60:61]
	s_mov_b32 m0, s42
	s_nop 0
	global_load_lds_dwordx4 v[192:193], off
	s_add_i32 s6, s6, s3
	v_lshl_add_u64 v[192:193], v[224:225], 0, s[60:61]
	s_mov_b32 m0, s6
	s_nop 0
	global_load_lds_dwordx4 v[192:193], off
	v_lshl_add_u64 v[192:193], v[226:227], 0, s[60:61]
	s_add_i32 m0, s6, 0x2000
	s_nop 0
	global_load_lds_dwordx4 v[192:193], off
	s_waitcnt vmcnt(8)
	s_waitcnt lgkmcnt(0)
	s_barrier
	s_setprio 1
	v_mfma_f32_16x16x32_bf16 v[62:65], v[142:145], v[164:167], v[62:65]
	v_mfma_f32_16x16x32_bf16 v[58:61], v[150:153], v[164:167], v[58:61]
	v_mfma_f32_16x16x32_bf16 v[46:49], v[142:145], v[172:175], v[46:49]
	v_mfma_f32_16x16x32_bf16 v[42:45], v[150:153], v[172:175], v[42:45]
	v_mfma_f32_16x16x32_bf16 v[30:33], v[142:145], v[180:183], v[30:33]
	v_mfma_f32_16x16x32_bf16 v[26:29], v[150:153], v[180:183], v[26:29]
	v_mfma_f32_16x16x32_bf16 v[14:17], v[142:145], v[188:191], v[14:17]
	v_mfma_f32_16x16x32_bf16 v[10:13], v[150:153], v[188:191], v[10:13]
	v_mfma_f32_16x16x32_bf16 v[62:65], v[146:149], v[168:171], v[62:65]
	v_mfma_f32_16x16x32_bf16 v[58:61], v[160:163], v[168:171], v[58:61]
	v_mfma_f32_16x16x32_bf16 v[46:49], v[146:149], v[176:179], v[46:49]
	v_mfma_f32_16x16x32_bf16 v[42:45], v[160:163], v[176:179], v[42:45]
	v_mfma_f32_16x16x32_bf16 v[30:33], v[146:149], v[184:187], v[30:33]
	v_mfma_f32_16x16x32_bf16 v[26:29], v[160:163], v[184:187], v[26:29]
	v_mfma_f32_16x16x32_bf16 v[14:17], v[146:149], v[196:199], v[14:17]
	v_mfma_f32_16x16x32_bf16 v[10:13], v[160:163], v[196:199], v[10:13]
	v_mfma_f32_16x16x32_bf16 v[54:57], v[200:203], v[164:167], v[54:57]
	v_mfma_f32_16x16x32_bf16 v[50:53], v[208:211], v[164:167], v[50:53]
	v_mfma_f32_16x16x32_bf16 v[38:41], v[200:203], v[172:175], v[38:41]
	v_mfma_f32_16x16x32_bf16 v[34:37], v[208:211], v[172:175], v[34:37]
	v_mfma_f32_16x16x32_bf16 v[22:25], v[200:203], v[180:183], v[22:25]
	v_mfma_f32_16x16x32_bf16 v[18:21], v[208:211], v[180:183], v[18:21]
	v_mfma_f32_16x16x32_bf16 v[6:9], v[200:203], v[188:191], v[6:9]
	v_mfma_f32_16x16x32_bf16 v[2:5], v[208:211], v[188:191], v[2:5]
	v_mfma_f32_16x16x32_bf16 v[54:57], v[204:207], v[168:171], v[54:57]
	v_mfma_f32_16x16x32_bf16 v[50:53], v[212:215], v[168:171], v[50:53]
	v_mfma_f32_16x16x32_bf16 v[38:41], v[204:207], v[176:179], v[38:41]
	v_mfma_f32_16x16x32_bf16 v[34:37], v[212:215], v[176:179], v[34:37]
	v_mfma_f32_16x16x32_bf16 v[22:25], v[204:207], v[184:187], v[22:25]
	v_mfma_f32_16x16x32_bf16 v[18:21], v[212:215], v[184:187], v[18:21]
	v_mfma_f32_16x16x32_bf16 v[6:9], v[204:207], v[196:199], v[6:9]
	v_mfma_f32_16x16x32_bf16 v[2:5], v[212:215], v[196:199], v[2:5]
	s_setprio 0
	s_add_u32 s4, s4, 0x100
	s_addc_u32 s5, s5, 0
	s_add_u32 s34, s34, 0x100
	s_addc_u32 s35, s35, 0
	s_cmp_ge_u32 s14, s73
	s_mov_b32 s6, s14
	s_barrier
	s_cbranch_scc0 .LBB0_555
	v_and_or_b32 v142, v220, 64, v154
	v_lshlrev_b32_e32 v148, 2, v142
	ds_bpermute_b32 v143, v148, v141
	ds_bpermute_b32 v142, v148, v141 offset:64
	s_mov_b32 s4, 0x3a000000
	ds_bpermute_b32 v145, v148, v141 offset:128
	ds_bpermute_b32 v144, v148, v141 offset:192
	v_readlane_b32 s8, v254, 29
	s_waitcnt lgkmcnt(0)
	v_pk_fma_f32 v[146:147], v[142:143], s[4:5], v[232:233] op_sel_hi:[1,0,0]
	ds_bpermute_b32 v143, v148, v140
	v_mul_f32_e32 v141, 0x4b800000, v147
	v_cmp_gt_f32_e32 vcc, s97, v147
	ds_bpermute_b32 v142, v148, v140 offset:64
	v_readlane_b32 s9, v254, 30
	v_cndmask_b32_e32 v141, v147, v141, vcc
	v_rsq_f32_e32 v141, v141
	v_cmp_gt_f32_e64 s[4:5], s97, v146
	s_mov_b64 s[90:91], -1
	v_mul_f32_e32 v147, 0x45800000, v141
	v_cndmask_b32_e32 v141, v141, v147, vcc
	v_cndmask_b32_e64 v147, v141, 1.0, s[78:79]
	ds_bpermute_b32 v141, v148, v140 offset:128
	ds_bpermute_b32 v140, v148, v140 offset:192
	v_mul_f32_e32 v148, s70, v147
	v_pk_mul_f32 v[152:153], v[122:123], v[148:149] op_sel_hi:[1,0]
	v_cndmask_b32_e64 v122, 0, 1, s[8:9]
	v_pk_mul_f32 v[128:129], v[128:129], v[148:149] op_sel_hi:[1,0]
	v_pk_mul_f32 v[150:151], v[126:127], v[148:149] op_sel_hi:[1,0]
	v_pk_mul_f32 v[126:127], v[124:125], v[148:149] op_sel_hi:[1,0]
	v_cmp_ne_u32_e64 s[6:7], 1, v122
	s_andn2_b64 vcc, exec, s[8:9]
	s_cbranch_vccnz .LBB0_558
	s_mov_b64 s[90:91], 0

; __device__ __forceinline__ int otid() { int t = threadIdx.x; asm volatile("" : "+v"(t)); return t; }
; #define PG8_STAGE(bufoff, gbase, voff) do { _Pragma("unroll") for (int _i = 0; _i < 2; ++_i) \
;         __builtin_amdgcn_global_load_lds((const unsigned*)((const char*)(gbase) + (voff)[_i]), (LAS unsigned*)(lds + (bufoff) + ldsw + _i * 8192), 16, 0, 0); } while (0)
; #define PG8_WAIT_V(n) asm volatile("s_waitcnt vmcnt(" #n ")" ::: "memory")
; #define PG8_BAR __builtin_amdgcn_s_barrier()
;     __device__ __forceinline__ Pre prefetch(const Unit& u, int wr, int fr) const { return pre_rows(ss, u.pm * 256 + wr * 64 + (int)(threadIdx.x & 63)); }
;     __device__ __forceinline__ Pre prefetch(const Unit& u, int wr, int fr) const { return pre_rows(ss, u.pm * 256 + wr * 64 + (int)(threadIdx.x & 63)); }
; template <class Epi>
; __device__ __forceinline__ void gemm_phase(LAS unsigned char* lds, const Gemm g, const Sched& S, const Epi& E) {
;     const int tid = otid(), wid = __builtin_amdgcn_readfirstlane(tid >> 6), lane = tid & 63, wr = wid >> 2, wc = wid & 3, fr = lane & 15, fq = lane >> 4;
;     const int nt = g.K / BK;
;     unsigned voffA[2], voffB[2];
; #pragma unroll
;     for (int i = 0; i < 2; ++i) { int R, C; stage_rc(tid * 16 + i * 8192, R, C); const int Rb = Epi::PERM ? ((R & ~31) + perm32(R & 31)) : R;
;         voffA[i] = (unsigned)(R * g.lda + C) * 2u; voffB[i] = (unsigned)(Rb * g.ldb + C) * 2u; }
;     const size_t kstep = (size_t)(BK * 2);
;     const size_t hstepA = (size_t)HALF * g.lda * 2, hstepB = (size_t)HALF * g.ldb * 2;
;     const unsigned ldsw = (unsigned)wid * 1024u;
;     const int aoff = lds_byte(wr * 64 + fr, fq * 8), boff = lds_byte(wc * 32 + fr, fq * 8);
;     ...
;     PG8_STAGE(PG8_SB(0, 0), cB, voffB); PG8_STAGE(PG8_SA(0, 0), cA, voffA); PG8_STAGE(PG8_SB(0, 1), cB + hstepB, voffB); PG8_STAGE(PG8_SA(0, 1), cA + hstepA, voffA);
;     if (wr == 1) PG8_BAR;
;     PG8_WAIT_V(4); PG8_BAR;
;     PG8_STAGE(PG8_SB(1, 0), cB + kstep, voffB); PG8_STAGE(PG8_SA(1, 0), cA + kstep, voffA); PG8_STAGE(PG8_SB(1, 1), cB + hstepB + kstep, voffB);
;     PG8_WAIT_V(6); PG8_BAR;
;     for (;;) {
;         const Pre pre = E.prefetch(cur, wr, fr);
;         const bool has_next = S.next(ui + 1, nxt);
;         const char* nA = has_next ? (const char*)g.A + nxt.ao : cA; const char* nB = has_next ? (const char*)g.Bt + nxt.bo : cB;
.LBB0_635:
	s_add_i32 m0, s89, 0x18000
	v_lshl_add_u64 v[2:3], v[2:3], 0, s[60:61]
	s_waitcnt vmcnt(0)
	s_barrier
	global_load_lds_dwordx4 v[2:3], off
	v_lshl_add_u64 v[2:3], v[4:5], 0, s[60:61]
	s_add_i32 m0, s89, 0x1a000
	s_add_i32 s93, s89, 0x8000
	global_load_lds_dwordx4 v[2:3], off
	v_lshl_add_u64 v[2:3], v[6:7], 0, s[60:61]
	s_mov_b32 m0, s93
	s_add_i32 s94, s89, 0xa000
	global_load_lds_dwordx4 v[2:3], off
	v_lshl_add_u64 v[2:3], v[8:9], 0, s[60:61]
	s_mov_b32 m0, s94
	v_lshrrev_b32_e32 v20, 1, v0
	global_load_lds_dwordx4 v[2:3], off
	s_add_i32 m0, s89, 0x1c000
	v_lshl_add_u64 v[2:3], v[10:11], 0, s[60:61]
	global_load_lds_dwordx4 v[2:3], off
	v_lshl_add_u64 v[2:3], v[12:13], 0, s[60:61]
	s_add_i32 m0, s89, 0x1e000
	v_and_b32_e32 v20, 24, v20
	global_load_lds_dwordx4 v[2:3], off
	v_and_b32_e32 v234, 15, v0
	v_lshlrev_b32_e32 v21, 1, v20
	v_lshlrev_b32_e32 v0, 2, v0
	s_and_b32 s8, s2, 3
	s_lshl_b32 s9, s14, 6
	v_lshl_or_b32 v21, v234, 6, v21
	s_lshl_b32 s14, s14, 13
	v_and_b32_e32 v0, 32, v0
	v_bitop3_b32 v22, v21, s14, v0 bitop3:0xde
	s_lshl_b32 s14, s8, 5
	s_lshl_b32 s8, s8, 12
	v_bitop3_b32 v236, v21, s8, v0 bitop3:0xde
	v_and_b32_e32 v0, 63, v219
	v_or_b32_e32 v235, s9, v234
	v_or_b32_e32 v237, s9, v0
	s_lshl_b32 s2, s2, 6
	v_readlane_b32 s8, v253, 61
	s_add_i32 s95, s73, -2
	s_and_b32 s2, s2, 0x80
	v_readlane_b32 s9, v253, 62
	s_cmp_eq_u64 s[8:9], 0
	s_cselect_b64 s[76:77], -1, 0
	s_cmp_lg_u64 s[8:9], 0
	v_readlane_b32 s8, v254, 13
	s_cselect_b64 s[78:79], -1, 0
	s_ashr_i32 s96, s8, 31
	s_lshr_b32 s8, s54, 3
	v_and_or_b32 v2, s14, 32, v20
	v_writelane_b32 v253, s8, 30
	s_add_i32 s65, s8, 1
	v_readlane_b32 s8, v254, 5
	v_readlane_b32 s9, v254, 37
	s_mul_i32 s97, s8, s9
	v_lshlrev_b32_e32 v0, 3, v2
	v_lshl_add_u64 v[186:187], s[84:85], 0, v[0:1]
	v_cvt_f32_u32_e32 v0, s97
	s_sub_i32 s8, 0, s97
	s_waitcnt vmcnt(6)
	v_or_b32_e32 v238, s14, v20
	v_rcp_iflag_f32_e32 v0, v0
	s_mov_b32 s27, s39
	s_and_b32 s71, s54, 7
	s_mov_b32 s67, s39
	v_mul_f32_e32 v0, 0x4f7ffffe, v0
	v_cvt_u32_f32_e32 v0, v0
	s_mov_b32 s42, 0
	v_add_u32_e32 v239, 0, v22
	s_lshl_b32 s66, s2, 1
	v_readfirstlane_b32 s9, v0
	v_cvt_f32_u32_e32 v0, s25
	s_mul_i32 s8, s8, s9
	s_mul_hi_u32 s8, s9, s8
	s_add_i32 s43, s9, s8
	v_rcp_iflag_f32_e32 v0, v0
	s_sub_i32 s8, 0, s25
	s_barrier
	v_mul_f32_e32 v0, 0x4f7ffffe, v0
	v_cvt_u32_f32_e32 v0, v0
	s_nop 0
	v_readfirstlane_b32 s9, v0
	v_add_u32_e32 v0, v16, v14
	v_add_lshl_u32 v0, v0, v15, 1
	s_mul_i32 s8, s8, s9
	v_lshl_add_u64 v[188:189], s[6:7], 0, v[0:1]
	v_add_u32_e32 v0, v19, v17
	s_mul_hi_u32 s8, s9, s8
	v_add_lshl_u32 v0, v0, v18, 1
	s_add_i32 s52, s9, s8
	v_lshl_add_u64 v[190:191], s[6:7], 0, v[0:1]
	v_lshlrev_b32_e32 v0, 1, v2
	s_branch .LBB0_637

; #define PG8_STAGE(bufoff, gbase, voff) do { _Pragma("unroll") for (int _i = 0; _i < 2; ++_i) \
;         __builtin_amdgcn_global_load_lds((const unsigned*)((const char*)(gbase) + (voff)[_i]), (LAS unsigned*)(lds + (bufoff) + ldsw + _i * 8192), 16, 0, 0); } while (0)
; #define PG8_LDA(dst, b, h) do { _Pragma("unroll") for (int m = 0; m < 4; ++m) _Pragma("unroll") for (int k = 0; k < 2; ++k) dst[m][k] = *(const LAS bf16x8*)(lds + PG8_SA(b, h) + aoff + m * 2048 + k * 1024); } while (0)
; #define PG8_LDB(dst, b, h) do { _Pragma("unroll") for (int n = 0; n < 2; ++n) _Pragma("unroll") for (int k = 0; k < 2; ++k) dst[n][k] = *(const LAS bf16x8*)(lds + PG8_SB(b, h) + boff + n * 2048 + k * 1024); } while (0)
; #define PG8_MMA(ai, bj, At, Bt) do { __builtin_amdgcn_s_setprio(1); _Pragma("unroll") for (int m = 0; m < 4; ++m) _Pragma("unroll") for (int n = 0; n < 2; ++n) _Pragma("unroll") for (int k = 0; k < 2; ++k) \
;         acc[ai][bj][m][n] = __builtin_amdgcn_mfma_f32_16x16x32_bf16(Bt[n][k], At[m][k], acc[ai][bj][m][n], 0, 0, 0); __builtin_amdgcn_s_setprio(0); } while (0)
; #define PG8_WAIT_L(n) asm volatile("s_waitcnt lgkmcnt(" #n ")" ::: "memory")
; #define PG8_BAR __builtin_amdgcn_s_barrier()
; #define PG8_SCHED __builtin_amdgcn_sched_barrier(0)
; template <class Epi>
; __device__ __forceinline__ void gemm_phase(LAS unsigned char* lds, const Gemm g, const Sched& S, const Epi& E) {
;     ...
;         for (int t = 0; t < nt; t += 2) {
;             const bool last = (t == nt - 2);
;             const char* a1 = cA + (size_t)(t + 1) * kstep;
;             const char* a2 = last ? nA : cA + (size_t)(t + 2) * kstep; const char* b2 = last ? nB : cB + (size_t)(t + 2) * kstep;
;             const char* a3 = a2 + kstep; const char* b3 = b2 + kstep;
;             PG8_LDB(B0, 0, 0); PG8_SCHED; PG8_LDA(At, 0, 0); PG8_STAGE(PG8_SA(1, 1), a1 + hstepA, voffA);
;             PG8_WAIT_L(8); PG8_BAR; PG8_WAIT_L(0); PG8_MMA(0, 0, At, B0); PG8_BAR; PG8_SCHED;
;             PG8_LDB(B1, 0, 1); PG8_STAGE(PG8_SB(0, 0), b2, voffB);
;             PG8_BAR; PG8_WAIT_L(0); PG8_MMA(0, 1, At, B1); PG8_BAR;
;             PG8_LDA(At, 0, 1); PG8_STAGE(PG8_SA(0, 0), a2, voffA);
.LBB0_649:
	s_add_i32 s14, s4, 2
	s_add_u32 s8, s0, 0x80
	s_addc_u32 s5, s1, 0
	s_add_i32 s9, 0, 0x10000
	v_add_u32_e32 v144, s9, v236
	ds_read_b128 v[132:135], v144
	ds_read_b128 v[136:139], v144 offset:1024
	ds_read_b128 v[140:143], v144 offset:2048
	ds_read_b128 v[144:147], v144 offset:3072
	s_cmp_eq_u32 s95, s4
	s_cselect_b32 s4, s48, s8
	s_cselect_b32 s5, s33, s5
	s_cselect_b32 s87, s51, s35
	s_cselect_b32 s86, s55, s34
	v_lshl_add_u64 v[176:177], s[0:1], 0, v[188:189]
	s_add_i32 m0, s89, 0xc000
	ds_read_b128 v[148:151], v239
	ds_read_b128 v[152:155], v239 offset:1024
	ds_read_b128 v[156:159], v239 offset:2048
	ds_read_b128 v[160:163], v239 offset:3072
	ds_read_b128 v[164:167], v239 offset:4096
	ds_read_b128 v[168:171], v239 offset:5120
	ds_read_b128 v[172:175], v239 offset:6144
	ds_read_b128 v[196:199], v239 offset:7168
	global_load_lds_dwordx4 v[176:177], off
	v_lshl_add_u64 v[176:177], s[0:1], 0, v[190:191]
	s_add_i32 m0, s89, 0xe000
	s_nop 0
	global_load_lds_dwordx4 v[176:177], off
	s_add_i32 s8, 0, 0x14000
	v_add_u32_e32 v176, s8, v236
	ds_read_b128 v[200:203], v176
	ds_read_b128 v[204:207], v176 offset:1024
	ds_read_b128 v[208:211], v176 offset:2048
	ds_read_b128 v[212:215], v176 offset:3072
	s_waitcnt vmcnt(8)
	s_waitcnt lgkmcnt(0)
	s_barrier
	s_setprio 1
	v_mfma_f32_16x16x32_bf16 v[126:129], v[132:135], v[148:151], v[126:129]
	v_mfma_f32_16x16x32_bf16 v[122:125], v[140:143], v[148:151], v[122:125]
	v_mfma_f32_16x16x32_bf16 v[110:113], v[132:135], v[156:159], v[110:113]
	v_mfma_f32_16x16x32_bf16 v[106:109], v[140:143], v[156:159], v[106:109]
	v_mfma_f32_16x16x32_bf16 v[94:97], v[132:135], v[164:167], v[94:97]
	v_mfma_f32_16x16x32_bf16 v[90:93], v[140:143], v[164:167], v[90:93]
	v_mfma_f32_16x16x32_bf16 v[78:81], v[132:135], v[172:175], v[78:81]
	v_mfma_f32_16x16x32_bf16 v[74:77], v[140:143], v[172:175], v[74:77]
	v_mfma_f32_16x16x32_bf16 v[126:129], v[136:139], v[152:155], v[126:129]
	v_mfma_f32_16x16x32_bf16 v[122:125], v[144:147], v[152:155], v[122:125]
	v_mfma_f32_16x16x32_bf16 v[110:113], v[136:139], v[160:163], v[110:113]
	v_mfma_f32_16x16x32_bf16 v[106:109], v[144:147], v[160:163], v[106:109]
	v_mfma_f32_16x16x32_bf16 v[94:97], v[136:139], v[168:171], v[94:97]
	v_mfma_f32_16x16x32_bf16 v[90:93], v[144:147], v[168:171], v[90:93]
	v_mfma_f32_16x16x32_bf16 v[78:81], v[136:139], v[196:199], v[78:81]
	v_mfma_f32_16x16x32_bf16 v[74:77], v[144:147], v[196:199], v[74:77]
	v_mfma_f32_16x16x32_bf16 v[118:121], v[200:203], v[148:151], v[118:121]
	v_mfma_f32_16x16x32_bf16 v[114:117], v[208:211], v[148:151], v[114:117]
	v_mfma_f32_16x16x32_bf16 v[102:105], v[200:203], v[156:159], v[102:105]
	v_mfma_f32_16x16x32_bf16 v[98:101], v[208:211], v[156:159], v[98:101]
	v_mfma_f32_16x16x32_bf16 v[86:89], v[200:203], v[164:167], v[86:89]
	v_mfma_f32_16x16x32_bf16 v[82:85], v[208:211], v[164:167], v[82:85]
	v_mfma_f32_16x16x32_bf16 v[70:73], v[200:203], v[172:175], v[70:73]
	v_mfma_f32_16x16x32_bf16 v[66:69], v[208:211], v[172:175], v[66:69]
	v_mfma_f32_16x16x32_bf16 v[118:121], v[204:207], v[152:155], v[118:121]
	v_mfma_f32_16x16x32_bf16 v[114:117], v[212:215], v[152:155], v[114:117]
	v_mfma_f32_16x16x32_bf16 v[102:105], v[204:207], v[160:163], v[102:105]
	v_mfma_f32_16x16x32_bf16 v[98:101], v[212:215], v[160:163], v[98:101]
	v_mfma_f32_16x16x32_bf16 v[86:89], v[204:207], v[168:171], v[86:89]
	v_mfma_f32_16x16x32_bf16 v[82:85], v[212:215], v[168:171], v[82:85]
	v_mfma_f32_16x16x32_bf16 v[70:73], v[204:207], v[196:199], v[70:73]
	v_mfma_f32_16x16x32_bf16 v[66:69], v[212:215], v[196:199], v[66:69]
	s_setprio 0
	s_barrier
	s_add_i32 s9, s9, s88
	v_lshl_add_u64 v[176:177], s[86:87], 0, v[180:181]
	s_mov_b32 m0, s9
	v_lshl_add_u64 v[192:193], s[86:87], 0, v[184:185]
	global_load_lds_dwordx4 v[176:177], off
	s_add_i32 m0, s9, 0x2000
	s_nop 0
	global_load_lds_dwordx4 v[192:193], off
	s_mov_b32 m0, s89
	v_lshl_add_u64 v[194:195], s[4:5], 0, v[178:179]
	ds_read_b128 v[148:151], v239 offset:16384
	ds_read_b128 v[152:155], v239 offset:17408
	ds_read_b128 v[156:159], v239 offset:18432
	ds_read_b128 v[160:163], v239 offset:19456
	ds_read_b128 v[164:167], v239 offset:20480
	ds_read_b128 v[168:171], v239 offset:21504
	ds_read_b128 v[172:175], v239 offset:22528
	ds_read_b128 v[196:199], v239 offset:23552
	global_load_lds_dwordx4 v[194:195], off
	v_lshl_add_u64 v[216:217], s[4:5], 0, v[182:183]
	s_mov_b32 m0, s90
	s_nop 0
	global_load_lds_dwordx4 v[216:217], off
	s_add_u32 s56, s86, s36
	s_addc_u32 s57, s87, s37
	s_add_i32 s8, s8, s88
	v_lshl_add_u64 v[222:223], s[56:57], 0, v[180:181]
	s_mov_b32 m0, s8
	v_lshl_add_u64 v[224:225], s[56:57], 0, v[184:185]
	global_load_lds_dwordx4 v[222:223], off
	s_add_i32 m0, s8, 0x2000
	s_nop 0
	global_load_lds_dwordx4 v[224:225], off
	s_waitcnt vmcnt(8)
	s_waitcnt lgkmcnt(0)
	s_barrier
; #define PG8_STAGE(bufoff, gbase, voff) do { _Pragma("unroll") for (int _i = 0; _i < 2; ++_i) \
;         __builtin_amdgcn_global_load_lds((const unsigned*)((const char*)(gbase) + (voff)[_i]), (LAS unsigned*)(lds + (bufoff) + ldsw + _i * 8192), 16, 0, 0); } while (0)
; #define PG8_LDA(dst, b, h) do { _Pragma("unroll") for (int m = 0; m < 4; ++m) _Pragma("unroll") for (int k = 0; k < 2; ++k) dst[m][k] = *(const LAS bf16x8*)(lds + PG8_SA(b, h) + aoff + m * 2048 + k * 1024); } while (0)
; #define PG8_LDB(dst, b, h) do { _Pragma("unroll") for (int n = 0; n < 2; ++n) _Pragma("unroll") for (int k = 0; k < 2; ++k) dst[n][k] = *(const LAS bf16x8*)(lds + PG8_SB(b, h) + boff + n * 2048 + k * 1024); } while (0)
; #define PG8_MMA(ai, bj, At, Bt) do { __builtin_amdgcn_s_setprio(1); _Pragma("unroll") for (int m = 0; m < 4; ++m) _Pragma("unroll") for (int n = 0; n < 2; ++n) _Pragma("unroll") for (int k = 0; k < 2; ++k) \
;         acc[ai][bj][m][n] = __builtin_amdgcn_mfma_f32_16x16x32_bf16(Bt[n][k], At[m][k], acc[ai][bj][m][n], 0, 0, 0); __builtin_amdgcn_s_setprio(0); } while (0)
; #define PG8_WAIT_V(n) asm volatile("s_waitcnt vmcnt(" #n ")" ::: "memory")
; #define PG8_WAIT_L(n) asm volatile("s_waitcnt lgkmcnt(" #n ")" ::: "memory")
; #define PG8_BAR __builtin_amdgcn_s_barrier()
; #define PG8_SCHED __builtin_amdgcn_sched_barrier(0)
; template <class Epi>
; __device__ __forceinline__ void gemm_phase(LAS unsigned char* lds, const Gemm g, const Sched& S, const Epi& E) {
;     ...
;             PG8_BAR; PG8_WAIT_L(0); PG8_MMA(0, 1, At, B1); PG8_BAR;
;             PG8_LDA(At, 0, 1); PG8_STAGE(PG8_SA(0, 0), a2, voffA);
;             PG8_BAR; PG8_WAIT_L(0); PG8_MMA(1, 0, At, B0); PG8_BAR; PG8_SCHED;
;             PG8_STAGE(PG8_SB(0, 1), b2 + hstepB, voffB);
;             PG8_WAIT_V(6); PG8_BAR; PG8_MMA(1, 1, At, B1); PG8_BAR;
;             PG8_LDB(B0, 1, 0); PG8_SCHED; PG8_LDA(At, 1, 0); PG8_STAGE(PG8_SA(0, 1), a2 + hstepA, voffA);
;             PG8_WAIT_L(8); PG8_BAR; PG8_WAIT_L(0); PG8_MMA(0, 0, At, B0); PG8_BAR; PG8_SCHED;
	s_setprio 1
	v_mfma_f32_16x16x32_bf16 v[62:65], v[132:135], v[148:151], v[62:65]
	v_mfma_f32_16x16x32_bf16 v[58:61], v[140:143], v[148:151], v[58:61]
	v_mfma_f32_16x16x32_bf16 v[46:49], v[132:135], v[156:159], v[46:49]
	v_mfma_f32_16x16x32_bf16 v[42:45], v[140:143], v[156:159], v[42:45]
	v_mfma_f32_16x16x32_bf16 v[30:33], v[132:135], v[164:167], v[30:33]
	v_mfma_f32_16x16x32_bf16 v[26:29], v[140:143], v[164:167], v[26:29]
	v_mfma_f32_16x16x32_bf16 v[14:17], v[132:135], v[172:175], v[14:17]
	v_mfma_f32_16x16x32_bf16 v[10:13], v[140:143], v[172:175], v[10:13]
	v_mfma_f32_16x16x32_bf16 v[62:65], v[136:139], v[152:155], v[62:65]
	v_mfma_f32_16x16x32_bf16 v[58:61], v[144:147], v[152:155], v[58:61]
	v_mfma_f32_16x16x32_bf16 v[46:49], v[136:139], v[160:163], v[46:49]
	v_mfma_f32_16x16x32_bf16 v[42:45], v[144:147], v[160:163], v[42:45]
	v_mfma_f32_16x16x32_bf16 v[30:33], v[136:139], v[168:171], v[30:33]
	v_mfma_f32_16x16x32_bf16 v[26:29], v[144:147], v[168:171], v[26:29]
	v_mfma_f32_16x16x32_bf16 v[14:17], v[136:139], v[196:199], v[14:17]
	v_mfma_f32_16x16x32_bf16 v[10:13], v[144:147], v[196:199], v[10:13]
	v_mfma_f32_16x16x32_bf16 v[54:57], v[200:203], v[148:151], v[54:57]
	v_mfma_f32_16x16x32_bf16 v[50:53], v[208:211], v[148:151], v[50:53]
	v_mfma_f32_16x16x32_bf16 v[38:41], v[200:203], v[156:159], v[38:41]
	v_mfma_f32_16x16x32_bf16 v[34:37], v[208:211], v[156:159], v[34:37]
	v_mfma_f32_16x16x32_bf16 v[22:25], v[200:203], v[164:167], v[22:25]
	v_mfma_f32_16x16x32_bf16 v[18:21], v[208:211], v[164:167], v[18:21]
	v_mfma_f32_16x16x32_bf16 v[6:9], v[200:203], v[172:175], v[6:9]
	v_mfma_f32_16x16x32_bf16 v[2:5], v[208:211], v[172:175], v[2:5]
	v_mfma_f32_16x16x32_bf16 v[54:57], v[204:207], v[152:155], v[54:57]
	v_mfma_f32_16x16x32_bf16 v[50:53], v[212:215], v[152:155], v[50:53]
	v_mfma_f32_16x16x32_bf16 v[38:41], v[204:207], v[160:163], v[38:41]
	v_mfma_f32_16x16x32_bf16 v[34:37], v[212:215], v[160:163], v[34:37]
	v_mfma_f32_16x16x32_bf16 v[22:25], v[204:207], v[168:171], v[22:25]
	v_mfma_f32_16x16x32_bf16 v[18:21], v[212:215], v[168:171], v[18:21]
	v_mfma_f32_16x16x32_bf16 v[6:9], v[204:207], v[196:199], v[6:9]
	v_mfma_f32_16x16x32_bf16 v[2:5], v[212:215], v[196:199], v[2:5]
	s_setprio 0
	s_barrier
	s_add_i32 s8, 0, 0x18000
	v_add_u32_e32 v144, s8, v236
	ds_read_b128 v[132:135], v144
	ds_read_b128 v[136:139], v144 offset:1024
	ds_read_b128 v[140:143], v144 offset:2048
	ds_read_b128 v[144:147], v144 offset:3072
	s_add_u32 s4, s4, s6
	s_addc_u32 s5, s5, s7
	s_mov_b32 m0, s91
	v_lshl_add_u64 v[200:201], s[4:5], 0, v[178:179]
	ds_read_b128 v[148:151], v239 offset:32768
	ds_read_b128 v[152:155], v239 offset:33792
	ds_read_b128 v[156:159], v239 offset:34816
	ds_read_b128 v[160:163], v239 offset:35840
	ds_read_b128 v[164:167], v239 offset:36864
	ds_read_b128 v[168:171], v239 offset:37888
	ds_read_b128 v[172:175], v239 offset:38912
	ds_read_b128 v[196:199], v239 offset:39936
	global_load_lds_dwordx4 v[200:201], off
	v_lshl_add_u64 v[200:201], s[4:5], 0, v[182:183]
	s_mov_b32 m0, s92
	s_nop 0
	global_load_lds_dwordx4 v[200:201], off
	s_add_i32 s4, 0, 0x1c000
	v_add_u32_e32 v212, s4, v236
	ds_read_b128 v[200:203], v212
	ds_read_b128 v[204:207], v212 offset:1024
	ds_read_b128 v[208:211], v212 offset:2048
	ds_read_b128 v[212:215], v212 offset:3072
	s_waitcnt vmcnt(8)
	s_waitcnt lgkmcnt(0)
	s_barrier
	s_setprio 1
	v_mfma_f32_16x16x32_bf16 v[126:129], v[132:135], v[148:151], v[126:129]
	v_mfma_f32_16x16x32_bf16 v[122:125], v[140:143], v[148:151], v[122:125]
	v_mfma_f32_16x16x32_bf16 v[110:113], v[132:135], v[156:159], v[110:113]
	v_mfma_f32_16x16x32_bf16 v[106:109], v[140:143], v[156:159], v[106:109]
	v_mfma_f32_16x16x32_bf16 v[94:97], v[132:135], v[164:167], v[94:97]
	v_mfma_f32_16x16x32_bf16 v[90:93], v[140:143], v[164:167], v[90:93]
	v_mfma_f32_16x16x32_bf16 v[78:81], v[132:135], v[172:175], v[78:81]
	v_mfma_f32_16x16x32_bf16 v[74:77], v[140:143], v[172:175], v[74:77]
	v_mfma_f32_16x16x32_bf16 v[126:129], v[136:139], v[152:155], v[126:129]
	v_mfma_f32_16x16x32_bf16 v[122:125], v[144:147], v[152:155], v[122:125]
	v_mfma_f32_16x16x32_bf16 v[110:113], v[136:139], v[160:163], v[110:113]
	v_mfma_f32_16x16x32_bf16 v[106:109], v[144:147], v[160:163], v[106:109]
	v_mfma_f32_16x16x32_bf16 v[94:97], v[136:139], v[168:171], v[94:97]
	v_mfma_f32_16x16x32_bf16 v[90:93], v[144:147], v[168:171], v[90:93]
	v_mfma_f32_16x16x32_bf16 v[78:81], v[136:139], v[196:199], v[78:81]
	v_mfma_f32_16x16x32_bf16 v[74:77], v[144:147], v[196:199], v[74:77]
	v_mfma_f32_16x16x32_bf16 v[118:121], v[200:203], v[148:151], v[118:121]
	v_mfma_f32_16x16x32_bf16 v[114:117], v[208:211], v[148:151], v[114:117]
	v_mfma_f32_16x16x32_bf16 v[102:105], v[200:203], v[156:159], v[102:105]
	v_mfma_f32_16x16x32_bf16 v[98:101], v[208:211], v[156:159], v[98:101]
	v_mfma_f32_16x16x32_bf16 v[86:89], v[200:203], v[164:167], v[86:89]
	v_mfma_f32_16x16x32_bf16 v[82:85], v[208:211], v[164:167], v[82:85]
	v_mfma_f32_16x16x32_bf16 v[70:73], v[200:203], v[172:175], v[70:73]
	v_mfma_f32_16x16x32_bf16 v[66:69], v[208:211], v[172:175], v[66:69]
	v_mfma_f32_16x16x32_bf16 v[118:121], v[204:207], v[152:155], v[118:121]
	v_mfma_f32_16x16x32_bf16 v[114:117], v[212:215], v[152:155], v[114:117]
	v_mfma_f32_16x16x32_bf16 v[102:105], v[204:207], v[160:163], v[102:105]
	v_mfma_f32_16x16x32_bf16 v[98:101], v[212:215], v[160:163], v[98:101]
	v_mfma_f32_16x16x32_bf16 v[86:89], v[204:207], v[168:171], v[86:89]
	v_mfma_f32_16x16x32_bf16 v[82:85], v[212:215], v[168:171], v[82:85]
	v_mfma_f32_16x16x32_bf16 v[70:73], v[204:207], v[196:199], v[70:73]
	v_mfma_f32_16x16x32_bf16 v[66:69], v[212:215], v[196:199], v[66:69]
	s_setprio 0
	s_barrier
; #define PG8_STAGE(bufoff, gbase, voff) do { _Pragma("unroll") for (int _i = 0; _i < 2; ++_i) \
;         __builtin_amdgcn_global_load_lds((const unsigned*)((const char*)(gbase) + (voff)[_i]), (LAS unsigned*)(lds + (bufoff) + ldsw + _i * 8192), 16, 0, 0); } while (0)
; #define PG8_LDA(dst, b, h) do { _Pragma("unroll") for (int m = 0; m < 4; ++m) _Pragma("unroll") for (int k = 0; k < 2; ++k) dst[m][k] = *(const LAS bf16x8*)(lds + PG8_SA(b, h) + aoff + m * 2048 + k * 1024); } while (0)
; #define PG8_LDB(dst, b, h) do { _Pragma("unroll") for (int n = 0; n < 2; ++n) _Pragma("unroll") for (int k = 0; k < 2; ++k) dst[n][k] = *(const LAS bf16x8*)(lds + PG8_SB(b, h) + boff + n * 2048 + k * 1024); } while (0)
; #define PG8_MMA(ai, bj, At, Bt) do { __builtin_amdgcn_s_setprio(1); _Pragma("unroll") for (int m = 0; m < 4; ++m) _Pragma("unroll") for (int n = 0; n < 2; ++n) _Pragma("unroll") for (int k = 0; k < 2; ++k) \
;         acc[ai][bj][m][n] = __builtin_amdgcn_mfma_f32_16x16x32_bf16(Bt[n][k], At[m][k], acc[ai][bj][m][n], 0, 0, 0); __builtin_amdgcn_s_setprio(0); } while (0)
; template <class Epi>
; __device__ __forceinline__ void gemm_phase(LAS unsigned char* lds, const Gemm g, const Sched& S, const Epi& E) {
;     ...
;             PG8_LDB(B0, 1, 0); PG8_SCHED; PG8_LDA(At, 1, 0); PG8_STAGE(PG8_SA(0, 1), a2 + hstepA, voffA);
;             PG8_WAIT_L(8); PG8_BAR; PG8_WAIT_L(0); PG8_MMA(0, 0, At, B0); PG8_BAR; PG8_SCHED;
;             PG8_LDB(B1, 1, 1); PG8_STAGE(PG8_SB(1, 0), b3, voffB);
;             PG8_BAR; PG8_WAIT_L(0); PG8_MMA(0, 1, At, B1); PG8_BAR;
;             PG8_LDA(At, 1, 1); PG8_STAGE(PG8_SA(1, 0), a3, voffA);
;             PG8_BAR; PG8_WAIT_L(0); PG8_MMA(1, 0, At, B0); PG8_BAR; PG8_SCHED;
;             PG8_STAGE(PG8_SB(1, 1), b3 + hstepB, voffB);
;             PG8_WAIT_V(6); PG8_BAR; PG8_MMA(1, 1, At, B1); PG8_BAR;
;         }
;     __device__ __forceinline__ void operator()(const Acc& acc, const Unit& u, int wr, int wc, int fr, int fq, const Pre& pre) const {
;         const int tile = u.pn; int mode = 0; float scale0 = 1.f;
;         if (tile < 36) { const int tg = tile % 12; if (tg < 4) { mode = 1; scale0 = 0.08838834764831845f * LOG2E; } else if (tg < 8) mode = 1; }
;         else if (tile < 40) mode = 1;
;         else if (tile < 44) { mode = 1; scale0 = 0.08838834764831845f; }
;         else if (tile >= 52) mode = 2;
	s_add_i32 s5, s8, s88
	v_lshl_add_u64 v[176:177], v[176:177], 0, s[60:61]
	s_mov_b32 m0, s5
	s_nop 0
	global_load_lds_dwordx4 v[176:177], off
	v_lshl_add_u64 v[176:177], v[192:193], 0, s[60:61]
	s_add_i32 m0, s5, 0x2000
	s_nop 0
	global_load_lds_dwordx4 v[176:177], off
	s_mov_b32 m0, s93
	v_lshl_add_u64 v[176:177], v[194:195], 0, s[60:61]
	ds_read_b128 v[148:151], v239 offset:49152
	ds_read_b128 v[152:155], v239 offset:50176
	ds_read_b128 v[156:159], v239 offset:51200
	ds_read_b128 v[160:163], v239 offset:52224
	ds_read_b128 v[164:167], v239 offset:53248
	ds_read_b128 v[168:171], v239 offset:54272
	ds_read_b128 v[172:175], v239 offset:55296
	ds_read_b128 v[196:199], v239 offset:56320
	global_load_lds_dwordx4 v[176:177], off
	v_lshl_add_u64 v[176:177], v[216:217], 0, s[60:61]
	s_mov_b32 m0, s94
	s_nop 0
	global_load_lds_dwordx4 v[176:177], off
	s_add_i32 s4, s4, s88
	v_lshl_add_u64 v[176:177], v[222:223], 0, s[60:61]
	s_mov_b32 m0, s4
	s_nop 0
	global_load_lds_dwordx4 v[176:177], off
	v_lshl_add_u64 v[176:177], v[224:225], 0, s[60:61]
	s_add_i32 m0, s4, 0x2000
	s_nop 0
	global_load_lds_dwordx4 v[176:177], off
	s_waitcnt vmcnt(8)
	s_waitcnt lgkmcnt(0)
	s_barrier
	s_setprio 1
	v_mfma_f32_16x16x32_bf16 v[62:65], v[132:135], v[148:151], v[62:65]
	v_mfma_f32_16x16x32_bf16 v[58:61], v[140:143], v[148:151], v[58:61]
	v_mfma_f32_16x16x32_bf16 v[46:49], v[132:135], v[156:159], v[46:49]
	v_mfma_f32_16x16x32_bf16 v[42:45], v[140:143], v[156:159], v[42:45]
	v_mfma_f32_16x16x32_bf16 v[30:33], v[132:135], v[164:167], v[30:33]
	v_mfma_f32_16x16x32_bf16 v[26:29], v[140:143], v[164:167], v[26:29]
	v_mfma_f32_16x16x32_bf16 v[14:17], v[132:135], v[172:175], v[14:17]
	v_mfma_f32_16x16x32_bf16 v[10:13], v[140:143], v[172:175], v[10:13]
	v_mfma_f32_16x16x32_bf16 v[62:65], v[136:139], v[152:155], v[62:65]
	v_mfma_f32_16x16x32_bf16 v[58:61], v[144:147], v[152:155], v[58:61]
	v_mfma_f32_16x16x32_bf16 v[46:49], v[136:139], v[160:163], v[46:49]
	v_mfma_f32_16x16x32_bf16 v[42:45], v[144:147], v[160:163], v[42:45]
	v_mfma_f32_16x16x32_bf16 v[30:33], v[136:139], v[168:171], v[30:33]
	v_mfma_f32_16x16x32_bf16 v[26:29], v[144:147], v[168:171], v[26:29]
	v_mfma_f32_16x16x32_bf16 v[14:17], v[136:139], v[196:199], v[14:17]
	v_mfma_f32_16x16x32_bf16 v[10:13], v[144:147], v[196:199], v[10:13]
	v_mfma_f32_16x16x32_bf16 v[54:57], v[200:203], v[148:151], v[54:57]
	v_mfma_f32_16x16x32_bf16 v[50:53], v[208:211], v[148:151], v[50:53]
	v_mfma_f32_16x16x32_bf16 v[38:41], v[200:203], v[156:159], v[38:41]
	v_mfma_f32_16x16x32_bf16 v[34:37], v[208:211], v[156:159], v[34:37]
	v_mfma_f32_16x16x32_bf16 v[22:25], v[200:203], v[164:167], v[22:25]
	v_mfma_f32_16x16x32_bf16 v[18:21], v[208:211], v[164:167], v[18:21]
	v_mfma_f32_16x16x32_bf16 v[6:9], v[200:203], v[172:175], v[6:9]
	v_mfma_f32_16x16x32_bf16 v[2:5], v[208:211], v[172:175], v[2:5]
	v_mfma_f32_16x16x32_bf16 v[54:57], v[204:207], v[152:155], v[54:57]
	v_mfma_f32_16x16x32_bf16 v[50:53], v[212:215], v[152:155], v[50:53]
	v_mfma_f32_16x16x32_bf16 v[38:41], v[204:207], v[160:163], v[38:41]
	v_mfma_f32_16x16x32_bf16 v[34:37], v[212:215], v[160:163], v[34:37]
	v_mfma_f32_16x16x32_bf16 v[22:25], v[204:207], v[168:171], v[22:25]
	v_mfma_f32_16x16x32_bf16 v[18:21], v[212:215], v[168:171], v[18:21]
	v_mfma_f32_16x16x32_bf16 v[6:9], v[204:207], v[196:199], v[6:9]
	v_mfma_f32_16x16x32_bf16 v[2:5], v[212:215], v[196:199], v[2:5]
	s_setprio 0
	s_add_u32 s0, s0, 0x100
	s_addc_u32 s1, s1, 0
	s_add_u32 s34, s34, 0x100
	s_addc_u32 s35, s35, 0
	s_cmp_ge_u32 s14, s73
	s_mov_b32 s4, s14
	s_barrier
	s_cbranch_scc0 .LBB0_649
	s_cmp_gt_i32 s3, 35
	s_cbranch_scc0 .LBB0_652
	s_cmp_gt_u32 s3, 51
	s_cselect_b32 s8, 2, 0
	s_cmp_gt_u32 s3, 39
	s_cselect_b64 s[0:1], -1, 0
	s_cmp_lt_u32 s3, 44
	s_cselect_b64 s[14:15], -1, 0
	s_and_b64 s[4:5], s[14:15], exec
	s_cselect_b32 s4, 1, s8
	s_and_b64 vcc, s[0:1], s[14:15]
	v_mov_b32_e32 v132, 0x3db504f3
	v_cndmask_b32_e32 v240, 1.0, v132, vcc
	v_mov_b32_e32 v132, s4
	s_cbranch_execz .LBB0_653
	s_branch .LBB0_654
